# carry-scan phase hand-written: decay table staged in LDS, each GLA state chain split in two halves run by waves 0-3 / 4-7 with a state hand-over, LRU carry scan split in 8 segments per chain with a cr
# speedup vs baseline: 1.0084x; 1.0084x over previous
; __device__ __forceinline__ float bf2f(bf16_t b) { return __uint_as_float(((unsigned)b) << 16); }
; __device__ __forceinline__ bf16_t f2bf(float f) { unsigned u = __float_as_uint(f); return (bf16_t)((u + 0x7fffu + ((u >> 16) & 1u)) >> 16); }
; __device__ __forceinline__ int otid() { int t = threadIdx.x; asm volatile("" : "+v"(t)); return t; }
; __device__ __forceinline__ int obid() { int t = blockIdx.x; asm volatile("" : "+s"(t)); return t; }
; __device__ void phase_scan(const Params& p) {
;     unsigned char* ws = p.ws; const int tid = otid();
;     if (tid < 256) {
;         const bf16_t* __restrict__ uT = (const bf16_t*)(ws + WS_M); bf16_t* __restrict__ spT = (bf16_t*)(ws + WS_M + (size_t)S * D * 2); const float* __restrict__ dec = (const float*)(ws + WS_DEC);
;         for (int gid = obid() * 256 + tid; gid < 65536; gid += gridDim.x * 256) {
;             const int dir = gid >> 15, rem = gid & 32767, h = rem >> 13, vd = rem & 8191, d = vd & 63;
;             float s = 0.f;
;             const long step = dir ? -1 : 1; const int nfirst = dir ? NCH - 1 : 0;
;             const bf16_t* up = uT + ((size_t)(dir * NCH + nfirst) * 4 + h) * 8192 + vd; bf16_t* sp = spT + ((size_t)(dir * NCH + nfirst) * 4 + h) * 8192 + vd;
;             const float* dp = dec + ((size_t)(dir * NCH + nfirst) * 4 + h) * 64 + d;
; #pragma unroll 1
;             for (int st = 0; st < NCH; st += 64) {
;                 bf16_t ub[64]; float db[64];
; #pragma unroll
;                 for (int i = 0; i < 64; ++i) { ub[i] = up[(long)(st + i) * step * 32768]; db[i] = dp[(long)(st + i) * step * 256]; }
; #pragma unroll
;                 for (int i = 0; i < 64; ++i) { sp[(long)(st + i) * step * 32768] = f2bf(s); s = db[i] * s + bf2f(ub[i]); }
.LBB0_172:
	s_and_b64 vcc, exec, s[0:1]
	s_cbranch_vccz .LBB0_346
	s_cmp_gt_i32 s49, 1
	s_mov_b64 s[0:1], -1
	s_cbranch_scc0 .LBB0_349
	s_cmp_gt_i32 s49, 2
	s_cbranch_scc0 .LBB0_189
	v_writelane_b32 v184, s16, 0
	v_writelane_b32 v184, s17, 1
	v_writelane_b32 v184, s18, 2
	v_writelane_b32 v184, s19, 3
	v_writelane_b32 v184, s20, 4
	v_writelane_b32 v184, s21, 5
	v_writelane_b32 v184, s22, 6
	v_writelane_b32 v184, s23, 7
	v_writelane_b32 v184, s24, 8
	v_writelane_b32 v184, s25, 9
	v_writelane_b32 v184, s26, 10
	v_writelane_b32 v184, s27, 11
	v_writelane_b32 v184, s28, 12
	v_writelane_b32 v184, s29, 13
	v_writelane_b32 v184, s30, 14
	v_writelane_b32 v184, s31, 15
	v_readfirstlane_b32 s4, v245
	v_readlane_b32 s5, v254, 59
	v_readlane_b32 s6, v255, 0
	v_readlane_b32 s7, v255, 1
	s_lshr_b32 s4, s4, 6
	s_lshr_b32 s8, s5, 7
	s_bfe_u32 s9, s5, 0x20005
	v_and_b32_e32 v0, 63, v245
	v_lshrrev_b32_e32 v1, 4, v0
	s_mul_i32 s10, s8, 3
	v_and_b32_e32 v2, 15, v0
	v_xor_b32_e32 v1, s10, v1
	v_lshlrev_b32_e32 v1, 10, v1
	v_lshl_add_u32 v172, v2, 4, v1
	s_lshl_b32 s11, s4, 5
	s_sub_u32 s12, 0xfc, s11
	s_cmp_eq_u32 s8, 0
	s_cselect_b32 s11, s11, s12
	s_lshl_b32 s12, s8, 8
	s_add_u32 s11, s11, s12
	s_lshl_b32 s11, s11, 10
	s_lshl_b32 s12, s9, 8
	s_add_u32 s11, s11, s12
	s_add_u32 s11, s11, 0xd358000
	s_add_u32 s16, s6, s11
	s_addc_u32 s17, s7, 0
	s_cmp_eq_u32 s8, 0
	s_mov_b32 s18, 0xfffff000
	s_cselect_b32 s18, 0x1000, s18
	s_cselect_b32 s19, 0, -1
	s_lshl_b32 s10, s4, 13
	s_add_u32 s10, s10, 0x10000
	s_mov_b32 m0, s10
	s_nop 0
	global_load_lds_dwordx4 v172, s[16:17]
	s_add_u32 s16, s16, s18
	s_addc_u32 s17, s17, s19
	s_add_u32 m0, s10, 0x400
	s_nop 0
	global_load_lds_dwordx4 v172, s[16:17]
	s_add_u32 s16, s16, s18
	s_addc_u32 s17, s17, s19
	s_add_u32 m0, s10, 0x800
	s_nop 0
	global_load_lds_dwordx4 v172, s[16:17]
	s_add_u32 s16, s16, s18
	s_addc_u32 s17, s17, s19
	s_add_u32 m0, s10, 0xc00
	s_nop 0
	global_load_lds_dwordx4 v172, s[16:17]
	s_add_u32 s16, s16, s18
	s_addc_u32 s17, s17, s19
	s_add_u32 m0, s10, 0x1000
	s_nop 0
	global_load_lds_dwordx4 v172, s[16:17]
	s_add_u32 s16, s16, s18
	s_addc_u32 s17, s17, s19
	s_add_u32 m0, s10, 0x1400
	s_nop 0
	global_load_lds_dwordx4 v172, s[16:17]
	s_add_u32 s16, s16, s18
	s_addc_u32 s17, s17, s19
	s_add_u32 m0, s10, 0x1800
	s_nop 0
	global_load_lds_dwordx4 v172, s[16:17]
	s_add_u32 s16, s16, s18
	s_addc_u32 s17, s17, s19
	s_add_u32 m0, s10, 0x1c00
	s_nop 0
	global_load_lds_dwordx4 v172, s[16:17]
	s_lshr_b32 s14, s4, 2
	v_and_b32_e32 v1, 0xff, v245
	v_lshlrev_b32_e32 v7, 2, v1
	v_add_u32_e32 v7, 0x20000, v7
	v_lshlrev_b32_e32 v1, 1, v1
	v_lshlrev_b32_e32 v2, 2, v0
	s_lshl_b32 s10, s14, 15
	s_add_u32 s10, s10, 0x10000
	v_add_u32_e32 v2, s10, v2
	s_mul_i32 s10, s8, 0x1ff
	s_lshl_b32 s10, s10, 16
	s_lshl_b32 s11, s9, 14
	s_add_u32 s10, s10, s11
	s_and_b32 s11, s5, 31
	s_lshl_b32 s11, s11, 9
	s_add_u32 s10, s10, s11
	s_add_u32 s10, s10, 0x9058000
	s_add_u32 s16, s6, s10
	s_addc_u32 s17, s7, 0
	s_cmp_eq_u32 s8, 0
	s_mov_b32 s20, 0xffff0000
	s_cselect_b32 s20, 0x10000, s20
	s_cselect_b32 s21, 0, -1
	s_mov_b32 s10, 0xff800000
	s_cselect_b32 s10, 0x800000, s10
	s_cselect_b32 s11, 0, -1
	s_cmp_eq_u32 s14, 0
	s_cselect_b32 s10, 0, s10
	s_cselect_b32 s11, 0, s11
	s_add_u32 s16, s16, s10
	s_addc_u32 s17, s17, s11
	s_add_u32 s18, s16, 0x2000000
	s_addc_u32 s19, s17, 0
	v_mov_b32_e32 v3, 0
	s_cmp_eq_u32 s14, 0
	s_cbranch_scc0 .Lscan_half1
	global_load_ushort v8, v1, s[16:17]
	s_add_u32 s16, s16, s20
	s_addc_u32 s17, s17, s21
	global_load_ushort v9, v1, s[16:17]
	s_add_u32 s16, s16, s20
	s_addc_u32 s17, s17, s21
	global_load_ushort v10, v1, s[16:17]
	s_add_u32 s16, s16, s20
	s_addc_u32 s17, s17, s21
	global_load_ushort v11, v1, s[16:17]
	s_add_u32 s16, s16, s20
	s_addc_u32 s17, s17, s21
	global_load_ushort v12, v1, s[16:17]
	s_add_u32 s16, s16, s20
	s_addc_u32 s17, s17, s21
	global_load_ushort v13, v1, s[16:17]
	s_add_u32 s16, s16, s20
	s_addc_u32 s17, s17, s21
	global_load_ushort v14, v1, s[16:17]
	s_add_u32 s16, s16, s20
	s_addc_u32 s17, s17, s21
	global_load_ushort v15, v1, s[16:17]
	s_add_u32 s16, s16, s20
	s_addc_u32 s17, s17, s21
	global_load_ushort v16, v1, s[16:17]
	s_add_u32 s16, s16, s20
	s_addc_u32 s17, s17, s21
	global_load_ushort v17, v1, s[16:17]
	s_add_u32 s16, s16, s20
	s_addc_u32 s17, s17, s21
	global_load_ushort v18, v1, s[16:17]
	s_add_u32 s16, s16, s20
	s_addc_u32 s17, s17, s21
	global_load_ushort v19, v1, s[16:17]
	s_add_u32 s16, s16, s20
	s_addc_u32 s17, s17, s21
	global_load_ushort v20, v1, s[16:17]
	s_add_u32 s16, s16, s20
	s_addc_u32 s17, s17, s21
	global_load_ushort v21, v1, s[16:17]
	s_add_u32 s16, s16, s20
	s_addc_u32 s17, s17, s21
	global_load_ushort v22, v1, s[16:17]
	s_add_u32 s16, s16, s20
	s_addc_u32 s17, s17, s21
	global_load_ushort v23, v1, s[16:17]
	s_add_u32 s16, s16, s20
	s_addc_u32 s17, s17, s21
	global_load_ushort v24, v1, s[16:17]
	s_add_u32 s16, s16, s20
	s_addc_u32 s17, s17, s21
	global_load_ushort v25, v1, s[16:17]
	s_add_u32 s16, s16, s20
	s_addc_u32 s17, s17, s21
	global_load_ushort v26, v1, s[16:17]
	s_add_u32 s16, s16, s20
	s_addc_u32 s17, s17, s21
	global_load_ushort v27, v1, s[16:17]
	s_add_u32 s16, s16, s20
	s_addc_u32 s17, s17, s21
	global_load_ushort v28, v1, s[16:17]
	s_add_u32 s16, s16, s20
	s_addc_u32 s17, s17, s21
	global_load_ushort v29, v1, s[16:17]
	s_add_u32 s16, s16, s20
	s_addc_u32 s17, s17, s21
	global_load_ushort v30, v1, s[16:17]
	s_add_u32 s16, s16, s20
	s_addc_u32 s17, s17, s21
	global_load_ushort v31, v1, s[16:17]
	s_add_u32 s16, s16, s20
	s_addc_u32 s17, s17, s21
	global_load_ushort v32, v1, s[16:17]
	s_add_u32 s16, s16, s20
	s_addc_u32 s17, s17, s21
; __device__ void phase_scan(const Params& p) {
;     ...
;                 bf16_t ub[64]; float db[64];
; #pragma unroll
;                 for (int i = 0; i < 64; ++i) { ub[i] = up[(long)(st + i) * step * 32768]; db[i] = dp[(long)(st + i) * step * 256]; }
	global_load_ushort v33, v1, s[16:17]
	s_add_u32 s16, s16, s20
	s_addc_u32 s17, s17, s21
	global_load_ushort v34, v1, s[16:17]
	s_add_u32 s16, s16, s20
	s_addc_u32 s17, s17, s21
	global_load_ushort v35, v1, s[16:17]
	s_add_u32 s16, s16, s20
	s_addc_u32 s17, s17, s21
	global_load_ushort v36, v1, s[16:17]
	s_add_u32 s16, s16, s20
	s_addc_u32 s17, s17, s21
	global_load_ushort v37, v1, s[16:17]
	s_add_u32 s16, s16, s20
	s_addc_u32 s17, s17, s21
	global_load_ushort v38, v1, s[16:17]
	s_add_u32 s16, s16, s20
	s_addc_u32 s17, s17, s21
	global_load_ushort v39, v1, s[16:17]
	s_add_u32 s16, s16, s20
	s_addc_u32 s17, s17, s21
	global_load_ushort v40, v1, s[16:17]
	s_add_u32 s16, s16, s20
	s_addc_u32 s17, s17, s21
	global_load_ushort v41, v1, s[16:17]
	s_add_u32 s16, s16, s20
	s_addc_u32 s17, s17, s21
	global_load_ushort v42, v1, s[16:17]
	s_add_u32 s16, s16, s20
	s_addc_u32 s17, s17, s21
	global_load_ushort v43, v1, s[16:17]
	s_add_u32 s16, s16, s20
	s_addc_u32 s17, s17, s21
	global_load_ushort v44, v1, s[16:17]
	s_add_u32 s16, s16, s20
	s_addc_u32 s17, s17, s21
	global_load_ushort v45, v1, s[16:17]
	s_add_u32 s16, s16, s20
	s_addc_u32 s17, s17, s21
	global_load_ushort v46, v1, s[16:17]
	s_add_u32 s16, s16, s20
	s_addc_u32 s17, s17, s21
	global_load_ushort v47, v1, s[16:17]
	s_add_u32 s16, s16, s20
	s_addc_u32 s17, s17, s21
	global_load_ushort v48, v1, s[16:17]
	s_add_u32 s16, s16, s20
	s_addc_u32 s17, s17, s21
	global_load_ushort v49, v1, s[16:17]
	s_add_u32 s16, s16, s20
	s_addc_u32 s17, s17, s21
	global_load_ushort v50, v1, s[16:17]
	s_add_u32 s16, s16, s20
	s_addc_u32 s17, s17, s21
	global_load_ushort v51, v1, s[16:17]
	s_add_u32 s16, s16, s20
	s_addc_u32 s17, s17, s21
	global_load_ushort v52, v1, s[16:17]
	s_add_u32 s16, s16, s20
	s_addc_u32 s17, s17, s21
	global_load_ushort v53, v1, s[16:17]
	s_add_u32 s16, s16, s20
	s_addc_u32 s17, s17, s21
	global_load_ushort v54, v1, s[16:17]
	s_add_u32 s16, s16, s20
	s_addc_u32 s17, s17, s21
	global_load_ushort v55, v1, s[16:17]
	s_add_u32 s16, s16, s20
	s_addc_u32 s17, s17, s21
	global_load_ushort v56, v1, s[16:17]
	s_add_u32 s16, s16, s20
	s_addc_u32 s17, s17, s21
	global_load_ushort v57, v1, s[16:17]
	s_add_u32 s16, s16, s20
	s_addc_u32 s17, s17, s21
	global_load_ushort v58, v1, s[16:17]
	s_add_u32 s16, s16, s20
	s_addc_u32 s17, s17, s21
	global_load_ushort v59, v1, s[16:17]
	s_add_u32 s16, s16, s20
	s_addc_u32 s17, s17, s21
	global_load_ushort v60, v1, s[16:17]
	s_add_u32 s16, s16, s20
	s_addc_u32 s17, s17, s21
	global_load_ushort v61, v1, s[16:17]
	s_add_u32 s16, s16, s20
	s_addc_u32 s17, s17, s21
	global_load_ushort v62, v1, s[16:17]
	s_add_u32 s16, s16, s20
	s_addc_u32 s17, s17, s21
	global_load_ushort v63, v1, s[16:17]
	s_add_u32 s16, s16, s20
	s_addc_u32 s17, s17, s21
	global_load_ushort v64, v1, s[16:17]
	s_add_u32 s16, s16, s20
	s_addc_u32 s17, s17, s21
	global_load_ushort v65, v1, s[16:17]
	s_add_u32 s16, s16, s20
	s_addc_u32 s17, s17, s21
	global_load_ushort v66, v1, s[16:17]
	s_add_u32 s16, s16, s20
	s_addc_u32 s17, s17, s21
	global_load_ushort v67, v1, s[16:17]
	s_add_u32 s16, s16, s20
	s_addc_u32 s17, s17, s21
	global_load_ushort v68, v1, s[16:17]
	s_add_u32 s16, s16, s20
	s_addc_u32 s17, s17, s21
	global_load_ushort v69, v1, s[16:17]
	s_add_u32 s16, s16, s20
	s_addc_u32 s17, s17, s21
	global_load_ushort v70, v1, s[16:17]
	s_add_u32 s16, s16, s20
	s_addc_u32 s17, s17, s21
	global_load_ushort v71, v1, s[16:17]
	s_add_u32 s16, s16, s20
	s_addc_u32 s17, s17, s21
	global_load_ushort v72, v1, s[16:17]
	s_add_u32 s16, s16, s20
	s_addc_u32 s17, s17, s21
	global_load_ushort v73, v1, s[16:17]
	s_add_u32 s16, s16, s20
	s_addc_u32 s17, s17, s21
	global_load_ushort v74, v1, s[16:17]
	s_add_u32 s16, s16, s20
	s_addc_u32 s17, s17, s21
	global_load_ushort v75, v1, s[16:17]
	s_add_u32 s16, s16, s20
	s_addc_u32 s17, s17, s21
	global_load_ushort v76, v1, s[16:17]
	s_add_u32 s16, s16, s20
	s_addc_u32 s17, s17, s21
	global_load_ushort v77, v1, s[16:17]
	s_add_u32 s16, s16, s20
	s_addc_u32 s17, s17, s21
	global_load_ushort v78, v1, s[16:17]
	s_add_u32 s16, s16, s20
	s_addc_u32 s17, s17, s21
	global_load_ushort v79, v1, s[16:17]
	s_add_u32 s16, s16, s20
	s_addc_u32 s17, s17, s21
	global_load_ushort v80, v1, s[16:17]
	s_add_u32 s16, s16, s20
	s_addc_u32 s17, s17, s21
	global_load_ushort v81, v1, s[16:17]
	s_add_u32 s16, s16, s20
	s_addc_u32 s17, s17, s21
	global_load_ushort v82, v1, s[16:17]
	s_add_u32 s16, s16, s20
	s_addc_u32 s17, s17, s21
	global_load_ushort v83, v1, s[16:17]
	s_add_u32 s16, s16, s20
	s_addc_u32 s17, s17, s21
	global_load_ushort v84, v1, s[16:17]
	s_add_u32 s16, s16, s20
	s_addc_u32 s17, s17, s21
	global_load_ushort v85, v1, s[16:17]
	s_add_u32 s16, s16, s20
	s_addc_u32 s17, s17, s21
	global_load_ushort v86, v1, s[16:17]
	s_add_u32 s16, s16, s20
	s_addc_u32 s17, s17, s21
	global_load_ushort v87, v1, s[16:17]
	s_add_u32 s16, s16, s20
	s_addc_u32 s17, s17, s21
	global_load_ushort v88, v1, s[16:17]
	s_add_u32 s16, s16, s20
	s_addc_u32 s17, s17, s21
	global_load_ushort v89, v1, s[16:17]
	s_add_u32 s16, s16, s20
	s_addc_u32 s17, s17, s21
	global_load_ushort v90, v1, s[16:17]
	s_add_u32 s16, s16, s20
	s_addc_u32 s17, s17, s21
	global_load_ushort v91, v1, s[16:17]
	s_add_u32 s16, s16, s20
	s_addc_u32 s17, s17, s21
	global_load_ushort v92, v1, s[16:17]
	s_add_u32 s16, s16, s20
	s_addc_u32 s17, s17, s21
	global_load_ushort v93, v1, s[16:17]
	s_add_u32 s16, s16, s20
	s_addc_u32 s17, s17, s21
	global_load_ushort v94, v1, s[16:17]
	s_add_u32 s16, s16, s20
	s_addc_u32 s17, s17, s21
	global_load_ushort v95, v1, s[16:17]
	s_add_u32 s16, s16, s20
	s_addc_u32 s17, s17, s21
	global_load_ushort v96, v1, s[16:17]
; __device__ __forceinline__ int obid() { int t = blockIdx.x; asm volatile("" : "+s"(t)); return t; }
; __device__ void phase_scan(const Params& p) {
;     ...
;                 bf16_t ub[64]; float db[64];
; #pragma unroll
;                 for (int i = 0; i < 64; ++i) { ub[i] = up[(long)(st + i) * step * 32768]; db[i] = dp[(long)(st + i) * step * 256]; }
;     ...
;     } else if (tid < 384 && obid() < 8) {
;         const float* __restrict__ Aprod = (const float*)(ws + WS_AP); const float* __restrict__ Hend = (const float*)(ws + WS_HE); float* __restrict__ carry = (float*)(ws + WS_CA);
;         const int gid = obid() * 128 + (tid - 256); const int dir = gid >> 9, ch = gid & 511;
;         float hc = 0.f;
;         const long step = dir ? -1 : 1; const size_t base = (size_t)(dir * NCH + (dir ? NCH - 1 : 0)) * 512 + ch;
	s_add_u32 s16, s16, s20
	s_addc_u32 s17, s17, s21
	global_load_ushort v97, v1, s[16:17]
	s_add_u32 s16, s16, s20
	s_addc_u32 s17, s17, s21
	global_load_ushort v98, v1, s[16:17]
	s_add_u32 s16, s16, s20
	s_addc_u32 s17, s17, s21
	global_load_ushort v99, v1, s[16:17]
	s_add_u32 s16, s16, s20
	s_addc_u32 s17, s17, s21
	global_load_ushort v100, v1, s[16:17]
	s_add_u32 s16, s16, s20
	s_addc_u32 s17, s17, s21
	global_load_ushort v101, v1, s[16:17]
	s_add_u32 s16, s16, s20
	s_addc_u32 s17, s17, s21
	global_load_ushort v102, v1, s[16:17]
	s_add_u32 s16, s16, s20
	s_addc_u32 s17, s17, s21
	global_load_ushort v103, v1, s[16:17]
	s_add_u32 s16, s16, s20
	s_addc_u32 s17, s17, s21
	global_load_ushort v104, v1, s[16:17]
	s_add_u32 s16, s16, s20
	s_addc_u32 s17, s17, s21
	global_load_ushort v105, v1, s[16:17]
	s_add_u32 s16, s16, s20
	s_addc_u32 s17, s17, s21
	global_load_ushort v106, v1, s[16:17]
	s_add_u32 s16, s16, s20
	s_addc_u32 s17, s17, s21
	global_load_ushort v107, v1, s[16:17]
	s_add_u32 s16, s16, s20
	s_addc_u32 s17, s17, s21
	global_load_ushort v108, v1, s[16:17]
	s_add_u32 s16, s16, s20
	s_addc_u32 s17, s17, s21
	global_load_ushort v109, v1, s[16:17]
	s_add_u32 s16, s16, s20
	s_addc_u32 s17, s17, s21
	global_load_ushort v110, v1, s[16:17]
	s_add_u32 s16, s16, s20
	s_addc_u32 s17, s17, s21
	global_load_ushort v111, v1, s[16:17]
	s_add_u32 s16, s16, s20
	s_addc_u32 s17, s17, s21
	global_load_ushort v112, v1, s[16:17]
	s_add_u32 s16, s16, s20
	s_addc_u32 s17, s17, s21
	global_load_ushort v113, v1, s[16:17]
	s_add_u32 s16, s16, s20
	s_addc_u32 s17, s17, s21
	global_load_ushort v114, v1, s[16:17]
	s_add_u32 s16, s16, s20
	s_addc_u32 s17, s17, s21
	global_load_ushort v115, v1, s[16:17]
	s_add_u32 s16, s16, s20
	s_addc_u32 s17, s17, s21
	global_load_ushort v116, v1, s[16:17]
	s_add_u32 s16, s16, s20
	s_addc_u32 s17, s17, s21
	global_load_ushort v117, v1, s[16:17]
	s_add_u32 s16, s16, s20
	s_addc_u32 s17, s17, s21
	global_load_ushort v118, v1, s[16:17]
	s_add_u32 s16, s16, s20
	s_addc_u32 s17, s17, s21
	global_load_ushort v119, v1, s[16:17]
	s_add_u32 s16, s16, s20
	s_addc_u32 s17, s17, s21
	global_load_ushort v120, v1, s[16:17]
	s_add_u32 s16, s16, s20
	s_addc_u32 s17, s17, s21
	global_load_ushort v121, v1, s[16:17]
	s_add_u32 s16, s16, s20
	s_addc_u32 s17, s17, s21
	global_load_ushort v122, v1, s[16:17]
	s_add_u32 s16, s16, s20
	s_addc_u32 s17, s17, s21
	global_load_ushort v123, v1, s[16:17]
	s_add_u32 s16, s16, s20
	s_addc_u32 s17, s17, s21
	global_load_ushort v124, v1, s[16:17]
	s_add_u32 s16, s16, s20
	s_addc_u32 s17, s17, s21
	global_load_ushort v125, v1, s[16:17]
	s_add_u32 s16, s16, s20
	s_addc_u32 s17, s17, s21
	global_load_ushort v126, v1, s[16:17]
	s_add_u32 s16, s16, s20
	s_addc_u32 s17, s17, s21
	global_load_ushort v127, v1, s[16:17]
	s_add_u32 s16, s16, s20
	s_addc_u32 s17, s17, s21
	global_load_ushort v128, v1, s[16:17]
	s_add_u32 s16, s16, s20
	s_addc_u32 s17, s17, s21
	global_load_ushort v129, v1, s[16:17]
	s_add_u32 s16, s16, s20
	s_addc_u32 s17, s17, s21
	global_load_ushort v130, v1, s[16:17]
	s_add_u32 s16, s16, s20
	s_addc_u32 s17, s17, s21
	global_load_ushort v131, v1, s[16:17]
	s_add_u32 s16, s16, s20
	s_addc_u32 s17, s17, s21
	global_load_ushort v132, v1, s[16:17]
	s_add_u32 s16, s16, s20
	s_addc_u32 s17, s17, s21
	global_load_ushort v133, v1, s[16:17]
	s_add_u32 s16, s16, s20
	s_addc_u32 s17, s17, s21
	global_load_ushort v134, v1, s[16:17]
	s_add_u32 s16, s16, s20
	s_addc_u32 s17, s17, s21
	global_load_ushort v135, v1, s[16:17]
	s_waitcnt vmcnt(63)
	s_barrier
	s_branch .Lscan_steps
.Lscan_half1:
	s_cmp_lt_u32 s5, 32
	s_cbranch_scc1 .Lscan_lru
	global_load_ushort v8, v1, s[16:17]
	s_add_u32 s16, s16, s20
	s_addc_u32 s17, s17, s21
	global_load_ushort v9, v1, s[16:17]
	s_add_u32 s16, s16, s20
	s_addc_u32 s17, s17, s21
	global_load_ushort v10, v1, s[16:17]
	s_add_u32 s16, s16, s20
	s_addc_u32 s17, s17, s21
	global_load_ushort v11, v1, s[16:17]
	s_add_u32 s16, s16, s20
	s_addc_u32 s17, s17, s21
	global_load_ushort v12, v1, s[16:17]
	s_add_u32 s16, s16, s20
	s_addc_u32 s17, s17, s21
	global_load_ushort v13, v1, s[16:17]
	s_add_u32 s16, s16, s20
	s_addc_u32 s17, s17, s21
	global_load_ushort v14, v1, s[16:17]
	s_add_u32 s16, s16, s20
	s_addc_u32 s17, s17, s21
	global_load_ushort v15, v1, s[16:17]
	s_add_u32 s16, s16, s20
	s_addc_u32 s17, s17, s21
	global_load_ushort v16, v1, s[16:17]
	s_add_u32 s16, s16, s20
	s_addc_u32 s17, s17, s21
	global_load_ushort v17, v1, s[16:17]
	s_add_u32 s16, s16, s20
	s_addc_u32 s17, s17, s21
	global_load_ushort v18, v1, s[16:17]
	s_add_u32 s16, s16, s20
	s_addc_u32 s17, s17, s21
	global_load_ushort v19, v1, s[16:17]
	s_add_u32 s16, s16, s20
	s_addc_u32 s17, s17, s21
	global_load_ushort v20, v1, s[16:17]
	s_add_u32 s16, s16, s20
	s_addc_u32 s17, s17, s21
	global_load_ushort v21, v1, s[16:17]
	s_add_u32 s16, s16, s20
	s_addc_u32 s17, s17, s21
	global_load_ushort v22, v1, s[16:17]
	s_add_u32 s16, s16, s20
	s_addc_u32 s17, s17, s21
	global_load_ushort v23, v1, s[16:17]
	s_add_u32 s16, s16, s20
	s_addc_u32 s17, s17, s21
	global_load_ushort v24, v1, s[16:17]
	s_add_u32 s16, s16, s20
	s_addc_u32 s17, s17, s21
	global_load_ushort v25, v1, s[16:17]
	s_add_u32 s16, s16, s20
	s_addc_u32 s17, s17, s21
	global_load_ushort v26, v1, s[16:17]
	s_add_u32 s16, s16, s20
	s_addc_u32 s17, s17, s21
	global_load_ushort v27, v1, s[16:17]
	s_add_u32 s16, s16, s20
	s_addc_u32 s17, s17, s21
	global_load_ushort v28, v1, s[16:17]
	s_add_u32 s16, s16, s20
	s_addc_u32 s17, s17, s21
	global_load_ushort v29, v1, s[16:17]
	s_add_u32 s16, s16, s20
	s_addc_u32 s17, s17, s21
	global_load_ushort v30, v1, s[16:17]
	s_add_u32 s16, s16, s20
; __device__ void phase_scan(const Params& p) {
;     ...
;                 bf16_t ub[64]; float db[64];
; #pragma unroll
;                 for (int i = 0; i < 64; ++i) { ub[i] = up[(long)(st + i) * step * 32768]; db[i] = dp[(long)(st + i) * step * 256]; }
	s_addc_u32 s17, s17, s21
	global_load_ushort v31, v1, s[16:17]
	s_add_u32 s16, s16, s20
	s_addc_u32 s17, s17, s21
	global_load_ushort v32, v1, s[16:17]
	s_add_u32 s16, s16, s20
	s_addc_u32 s17, s17, s21
	global_load_ushort v33, v1, s[16:17]
	s_add_u32 s16, s16, s20
	s_addc_u32 s17, s17, s21
	global_load_ushort v34, v1, s[16:17]
	s_add_u32 s16, s16, s20
	s_addc_u32 s17, s17, s21
	global_load_ushort v35, v1, s[16:17]
	s_add_u32 s16, s16, s20
	s_addc_u32 s17, s17, s21
	global_load_ushort v36, v1, s[16:17]
	s_add_u32 s16, s16, s20
	s_addc_u32 s17, s17, s21
	global_load_ushort v37, v1, s[16:17]
	s_add_u32 s16, s16, s20
	s_addc_u32 s17, s17, s21
	global_load_ushort v38, v1, s[16:17]
	s_add_u32 s16, s16, s20
	s_addc_u32 s17, s17, s21
	global_load_ushort v39, v1, s[16:17]
	s_add_u32 s16, s16, s20
	s_addc_u32 s17, s17, s21
	global_load_ushort v40, v1, s[16:17]
	s_add_u32 s16, s16, s20
	s_addc_u32 s17, s17, s21
	global_load_ushort v41, v1, s[16:17]
	s_add_u32 s16, s16, s20
	s_addc_u32 s17, s17, s21
	global_load_ushort v42, v1, s[16:17]
	s_add_u32 s16, s16, s20
	s_addc_u32 s17, s17, s21
	global_load_ushort v43, v1, s[16:17]
	s_add_u32 s16, s16, s20
	s_addc_u32 s17, s17, s21
	global_load_ushort v44, v1, s[16:17]
	s_add_u32 s16, s16, s20
	s_addc_u32 s17, s17, s21
	global_load_ushort v45, v1, s[16:17]
	s_add_u32 s16, s16, s20
	s_addc_u32 s17, s17, s21
	global_load_ushort v46, v1, s[16:17]
	s_add_u32 s16, s16, s20
	s_addc_u32 s17, s17, s21
	global_load_ushort v47, v1, s[16:17]
	s_add_u32 s16, s16, s20
	s_addc_u32 s17, s17, s21
	global_load_ushort v48, v1, s[16:17]
	s_add_u32 s16, s16, s20
	s_addc_u32 s17, s17, s21
	global_load_ushort v49, v1, s[16:17]
	s_add_u32 s16, s16, s20
	s_addc_u32 s17, s17, s21
	global_load_ushort v50, v1, s[16:17]
	s_add_u32 s16, s16, s20
	s_addc_u32 s17, s17, s21
	global_load_ushort v51, v1, s[16:17]
	s_add_u32 s16, s16, s20
	s_addc_u32 s17, s17, s21
	global_load_ushort v52, v1, s[16:17]
	s_add_u32 s16, s16, s20
	s_addc_u32 s17, s17, s21
	global_load_ushort v53, v1, s[16:17]
	s_add_u32 s16, s16, s20
	s_addc_u32 s17, s17, s21
	global_load_ushort v54, v1, s[16:17]
	s_add_u32 s16, s16, s20
	s_addc_u32 s17, s17, s21
	global_load_ushort v55, v1, s[16:17]
	s_add_u32 s16, s16, s20
	s_addc_u32 s17, s17, s21
	global_load_ushort v56, v1, s[16:17]
	s_add_u32 s16, s16, s20
	s_addc_u32 s17, s17, s21
	global_load_ushort v57, v1, s[16:17]
	s_add_u32 s16, s16, s20
	s_addc_u32 s17, s17, s21
	global_load_ushort v58, v1, s[16:17]
	s_add_u32 s16, s16, s20
	s_addc_u32 s17, s17, s21
	global_load_ushort v59, v1, s[16:17]
	s_add_u32 s16, s16, s20
	s_addc_u32 s17, s17, s21
	global_load_ushort v60, v1, s[16:17]
	s_add_u32 s16, s16, s20
	s_addc_u32 s17, s17, s21
	global_load_ushort v61, v1, s[16:17]
	s_add_u32 s16, s16, s20
	s_addc_u32 s17, s17, s21
	global_load_ushort v62, v1, s[16:17]
	s_add_u32 s16, s16, s20
	s_addc_u32 s17, s17, s21
	global_load_ushort v63, v1, s[16:17]
	s_add_u32 s16, s16, s20
	s_addc_u32 s17, s17, s21
	global_load_ushort v64, v1, s[16:17]
	s_add_u32 s16, s16, s20
	s_addc_u32 s17, s17, s21
	global_load_ushort v65, v1, s[16:17]
	s_add_u32 s16, s16, s20
	s_addc_u32 s17, s17, s21
	global_load_ushort v66, v1, s[16:17]
	s_add_u32 s16, s16, s20
	s_addc_u32 s17, s17, s21
	global_load_ushort v67, v1, s[16:17]
	s_add_u32 s16, s16, s20
	s_addc_u32 s17, s17, s21
	global_load_ushort v68, v1, s[16:17]
	s_add_u32 s16, s16, s20
	s_addc_u32 s17, s17, s21
	global_load_ushort v69, v1, s[16:17]
	s_add_u32 s16, s16, s20
	s_addc_u32 s17, s17, s21
	global_load_ushort v70, v1, s[16:17]
	s_add_u32 s16, s16, s20
	s_addc_u32 s17, s17, s21
	global_load_ushort v71, v1, s[16:17]
	s_add_u32 s16, s16, s20
	s_addc_u32 s17, s17, s21
	global_load_ushort v72, v1, s[16:17]
	s_add_u32 s16, s16, s20
	s_addc_u32 s17, s17, s21
	global_load_ushort v73, v1, s[16:17]
	s_add_u32 s16, s16, s20
	s_addc_u32 s17, s17, s21
	global_load_ushort v74, v1, s[16:17]
	s_add_u32 s16, s16, s20
	s_addc_u32 s17, s17, s21
	global_load_ushort v75, v1, s[16:17]
	s_add_u32 s16, s16, s20
	s_addc_u32 s17, s17, s21
	global_load_ushort v76, v1, s[16:17]
	s_add_u32 s16, s16, s20
	s_addc_u32 s17, s17, s21
	global_load_ushort v77, v1, s[16:17]
	s_add_u32 s16, s16, s20
	s_addc_u32 s17, s17, s21
	global_load_ushort v78, v1, s[16:17]
	s_add_u32 s16, s16, s20
	s_addc_u32 s17, s17, s21
	global_load_ushort v79, v1, s[16:17]
	s_add_u32 s16, s16, s20
	s_addc_u32 s17, s17, s21
	global_load_ushort v80, v1, s[16:17]
	s_add_u32 s16, s16, s20
	s_addc_u32 s17, s17, s21
	global_load_ushort v81, v1, s[16:17]
	s_add_u32 s16, s16, s20
	s_addc_u32 s17, s17, s21
	global_load_ushort v82, v1, s[16:17]
	s_add_u32 s16, s16, s20
	s_addc_u32 s17, s17, s21
	global_load_ushort v83, v1, s[16:17]
	s_add_u32 s16, s16, s20
	s_addc_u32 s17, s17, s21
	global_load_ushort v84, v1, s[16:17]
	s_add_u32 s16, s16, s20
	s_addc_u32 s17, s17, s21
	global_load_ushort v85, v1, s[16:17]
	s_add_u32 s16, s16, s20
	s_addc_u32 s17, s17, s21
	global_load_ushort v86, v1, s[16:17]
	s_add_u32 s16, s16, s20
	s_addc_u32 s17, s17, s21
	global_load_ushort v87, v1, s[16:17]
	s_add_u32 s16, s16, s20
	s_addc_u32 s17, s17, s21
	global_load_ushort v88, v1, s[16:17]
	s_add_u32 s16, s16, s20
	s_addc_u32 s17, s17, s21
	global_load_ushort v89, v1, s[16:17]
	s_add_u32 s16, s16, s20
	s_addc_u32 s17, s17, s21
	global_load_ushort v90, v1, s[16:17]
	s_add_u32 s16, s16, s20
	s_addc_u32 s17, s17, s21
	global_load_ushort v91, v1, s[16:17]
	s_add_u32 s16, s16, s20
	s_addc_u32 s17, s17, s21
	global_load_ushort v92, v1, s[16:17]
	s_add_u32 s16, s16, s20
	s_addc_u32 s17, s17, s21
	global_load_ushort v93, v1, s[16:17]
	s_add_u32 s16, s16, s20
	s_addc_u32 s17, s17, s21
; __device__ __forceinline__ int obid() { int t = blockIdx.x; asm volatile("" : "+s"(t)); return t; }
; __device__ void phase_scan(const Params& p) {
;     ...
;     } else if (tid < 384 && obid() < 8) {
;         const float* __restrict__ Aprod = (const float*)(ws + WS_AP); const float* __restrict__ Hend = (const float*)(ws + WS_HE); float* __restrict__ carry = (float*)(ws + WS_CA);
;         const int gid = obid() * 128 + (tid - 256); const int dir = gid >> 9, ch = gid & 511;
;         float hc = 0.f;
;         const long step = dir ? -1 : 1; const size_t base = (size_t)(dir * NCH + (dir ? NCH - 1 : 0)) * 512 + ch;
; #pragma unroll 1
;         for (int st = 0; st < NCH; st += 64) {
;             float ab[64], hb[64];
; #pragma unroll
;             for (int i = 0; i < 64; ++i) { ab[i] = Aprod[base + (long)(st + i) * step * 512]; hb[i] = Hend[base + (long)(st + i) * step * 512]; }
	global_load_ushort v94, v1, s[16:17]
	s_add_u32 s16, s16, s20
	s_addc_u32 s17, s17, s21
	global_load_ushort v95, v1, s[16:17]
	s_add_u32 s16, s16, s20
	s_addc_u32 s17, s17, s21
	global_load_ushort v96, v1, s[16:17]
	s_add_u32 s16, s16, s20
	s_addc_u32 s17, s17, s21
	global_load_ushort v97, v1, s[16:17]
	s_add_u32 s16, s16, s20
	s_addc_u32 s17, s17, s21
	global_load_ushort v98, v1, s[16:17]
	s_add_u32 s16, s16, s20
	s_addc_u32 s17, s17, s21
	global_load_ushort v99, v1, s[16:17]
	s_add_u32 s16, s16, s20
	s_addc_u32 s17, s17, s21
	global_load_ushort v100, v1, s[16:17]
	s_add_u32 s16, s16, s20
	s_addc_u32 s17, s17, s21
	global_load_ushort v101, v1, s[16:17]
	s_add_u32 s16, s16, s20
	s_addc_u32 s17, s17, s21
	global_load_ushort v102, v1, s[16:17]
	s_add_u32 s16, s16, s20
	s_addc_u32 s17, s17, s21
	global_load_ushort v103, v1, s[16:17]
	s_add_u32 s16, s16, s20
	s_addc_u32 s17, s17, s21
	global_load_ushort v104, v1, s[16:17]
	s_add_u32 s16, s16, s20
	s_addc_u32 s17, s17, s21
	global_load_ushort v105, v1, s[16:17]
	s_add_u32 s16, s16, s20
	s_addc_u32 s17, s17, s21
	global_load_ushort v106, v1, s[16:17]
	s_add_u32 s16, s16, s20
	s_addc_u32 s17, s17, s21
	global_load_ushort v107, v1, s[16:17]
	s_add_u32 s16, s16, s20
	s_addc_u32 s17, s17, s21
	global_load_ushort v108, v1, s[16:17]
	s_add_u32 s16, s16, s20
	s_addc_u32 s17, s17, s21
	global_load_ushort v109, v1, s[16:17]
	s_add_u32 s16, s16, s20
	s_addc_u32 s17, s17, s21
	global_load_ushort v110, v1, s[16:17]
	s_add_u32 s16, s16, s20
	s_addc_u32 s17, s17, s21
	global_load_ushort v111, v1, s[16:17]
	s_add_u32 s16, s16, s20
	s_addc_u32 s17, s17, s21
	global_load_ushort v112, v1, s[16:17]
	s_add_u32 s16, s16, s20
	s_addc_u32 s17, s17, s21
	global_load_ushort v113, v1, s[16:17]
	s_add_u32 s16, s16, s20
	s_addc_u32 s17, s17, s21
	global_load_ushort v114, v1, s[16:17]
	s_add_u32 s16, s16, s20
	s_addc_u32 s17, s17, s21
	global_load_ushort v115, v1, s[16:17]
	s_add_u32 s16, s16, s20
	s_addc_u32 s17, s17, s21
	global_load_ushort v116, v1, s[16:17]
	s_add_u32 s16, s16, s20
	s_addc_u32 s17, s17, s21
	global_load_ushort v117, v1, s[16:17]
	s_add_u32 s16, s16, s20
	s_addc_u32 s17, s17, s21
	global_load_ushort v118, v1, s[16:17]
	s_add_u32 s16, s16, s20
	s_addc_u32 s17, s17, s21
	global_load_ushort v119, v1, s[16:17]
	s_add_u32 s16, s16, s20
	s_addc_u32 s17, s17, s21
	global_load_ushort v120, v1, s[16:17]
	s_add_u32 s16, s16, s20
	s_addc_u32 s17, s17, s21
	global_load_ushort v121, v1, s[16:17]
	s_add_u32 s16, s16, s20
	s_addc_u32 s17, s17, s21
	global_load_ushort v122, v1, s[16:17]
	s_add_u32 s16, s16, s20
	s_addc_u32 s17, s17, s21
	global_load_ushort v123, v1, s[16:17]
	s_add_u32 s16, s16, s20
	s_addc_u32 s17, s17, s21
	global_load_ushort v124, v1, s[16:17]
	s_add_u32 s16, s16, s20
	s_addc_u32 s17, s17, s21
	global_load_ushort v125, v1, s[16:17]
	s_add_u32 s16, s16, s20
	s_addc_u32 s17, s17, s21
	global_load_ushort v126, v1, s[16:17]
	s_add_u32 s16, s16, s20
	s_addc_u32 s17, s17, s21
	global_load_ushort v127, v1, s[16:17]
	s_add_u32 s16, s16, s20
	s_addc_u32 s17, s17, s21
	global_load_ushort v128, v1, s[16:17]
	s_add_u32 s16, s16, s20
	s_addc_u32 s17, s17, s21
	global_load_ushort v129, v1, s[16:17]
	s_add_u32 s16, s16, s20
	s_addc_u32 s17, s17, s21
	global_load_ushort v130, v1, s[16:17]
	s_add_u32 s16, s16, s20
	s_addc_u32 s17, s17, s21
	global_load_ushort v131, v1, s[16:17]
	s_add_u32 s16, s16, s20
	s_addc_u32 s17, s17, s21
	global_load_ushort v132, v1, s[16:17]
	s_add_u32 s16, s16, s20
	s_addc_u32 s17, s17, s21
	global_load_ushort v133, v1, s[16:17]
	s_add_u32 s16, s16, s20
	s_addc_u32 s17, s17, s21
	global_load_ushort v134, v1, s[16:17]
	s_add_u32 s16, s16, s20
	s_addc_u32 s17, s17, s21
	global_load_ushort v135, v1, s[16:17]
	s_waitcnt vmcnt(63)
	s_barrier
	s_branch .Lscan_second
.Lscan_lru:
	s_waitcnt vmcnt(0)
	s_barrier
	s_lshl_b32 s10, s5, 2
	s_add_u32 s10, s10, s4
	s_sub_u32 s10, s10, 4
	s_lshr_b32 s11, s5, 4
	s_and_b32 s10, s10, 63
	s_lshl_b32 s10, s10, 5
	v_lshrrev_b32_e32 v75, 3, v0
	v_lshlrev_b32_e32 v76, 5, v75
	s_mul_i32 s12, s11, 0xff
	v_and_b32_e32 v77, 7, v0
	v_xor_b32_e32 v76, s12, v76
	v_lshlrev_b32_e32 v76, 11, v76
	v_lshl_add_u32 v74, v77, 2, v76
	v_add_u32_e32 v74, s10, v74
	s_lshl_b32 s12, s11, 19
	s_add_u32 s12, s12, 0xd058000
	s_add_u32 s24, s6, s12
	s_addc_u32 s25, s7, 0
	s_add_u32 s26, s24, 0x100000
	s_addc_u32 s27, s25, 0
	s_add_u32 s28, s24, 0x200000
	s_addc_u32 s29, s25, 0
	s_cmp_eq_u32 s11, 0
	s_mov_b32 s30, 0xfffff800
	s_cselect_b32 s30, 0x800, s30
	s_cselect_b32 s31, 0, -1
	global_load_dword v8, v74, s[24:25]
	global_load_dword v40, v74, s[26:27]
	s_add_u32 s24, s24, s30
	s_addc_u32 s25, s25, s31
	s_add_u32 s26, s26, s30
	s_addc_u32 s27, s27, s31
	global_load_dword v9, v74, s[24:25]
	global_load_dword v41, v74, s[26:27]
	s_add_u32 s24, s24, s30
	s_addc_u32 s25, s25, s31
	s_add_u32 s26, s26, s30
	s_addc_u32 s27, s27, s31
	global_load_dword v10, v74, s[24:25]
	global_load_dword v42, v74, s[26:27]
	s_add_u32 s24, s24, s30
	s_addc_u32 s25, s25, s31
	s_add_u32 s26, s26, s30
	s_addc_u32 s27, s27, s31
	global_load_dword v11, v74, s[24:25]
	global_load_dword v43, v74, s[26:27]
	s_add_u32 s24, s24, s30
	s_addc_u32 s25, s25, s31
	s_add_u32 s26, s26, s30
	s_addc_u32 s27, s27, s31
	global_load_dword v12, v74, s[24:25]
	global_load_dword v44, v74, s[26:27]
	s_add_u32 s24, s24, s30
	s_addc_u32 s25, s25, s31
	s_add_u32 s26, s26, s30
	s_addc_u32 s27, s27, s31
	global_load_dword v13, v74, s[24:25]
	global_load_dword v45, v74, s[26:27]
	s_add_u32 s24, s24, s30
	s_addc_u32 s25, s25, s31
	s_add_u32 s26, s26, s30
	s_addc_u32 s27, s27, s31
	global_load_dword v14, v74, s[24:25]
	global_load_dword v46, v74, s[26:27]
; __device__ __forceinline__ int obid() { int t = blockIdx.x; asm volatile("" : "+s"(t)); return t; }
; __device__ void phase_scan(const Params& p) {
;     ...
;         const float* __restrict__ Aprod = (const float*)(ws + WS_AP); const float* __restrict__ Hend = (const float*)(ws + WS_HE); float* __restrict__ carry = (float*)(ws + WS_CA);
;         const int gid = obid() * 128 + (tid - 256); const int dir = gid >> 9, ch = gid & 511;
;         float hc = 0.f;
;         const long step = dir ? -1 : 1; const size_t base = (size_t)(dir * NCH + (dir ? NCH - 1 : 0)) * 512 + ch;
; #pragma unroll 1
;         for (int st = 0; st < NCH; st += 64) {
;             float ab[64], hb[64];
; #pragma unroll
;             for (int i = 0; i < 64; ++i) { ab[i] = Aprod[base + (long)(st + i) * step * 512]; hb[i] = Hend[base + (long)(st + i) * step * 512]; }
; #pragma unroll
;             for (int i = 0; i < 64; ++i) { carry[base + (long)(st + i) * step * 512] = hc; hc = ab[i] * hc + hb[i]; }
;         }
	s_add_u32 s24, s24, s30
	s_addc_u32 s25, s25, s31
	s_add_u32 s26, s26, s30
	s_addc_u32 s27, s27, s31
	global_load_dword v15, v74, s[24:25]
	global_load_dword v47, v74, s[26:27]
	s_add_u32 s24, s24, s30
	s_addc_u32 s25, s25, s31
	s_add_u32 s26, s26, s30
	s_addc_u32 s27, s27, s31
	global_load_dword v16, v74, s[24:25]
	global_load_dword v48, v74, s[26:27]
	s_add_u32 s24, s24, s30
	s_addc_u32 s25, s25, s31
	s_add_u32 s26, s26, s30
	s_addc_u32 s27, s27, s31
	global_load_dword v17, v74, s[24:25]
	global_load_dword v49, v74, s[26:27]
	s_add_u32 s24, s24, s30
	s_addc_u32 s25, s25, s31
	s_add_u32 s26, s26, s30
	s_addc_u32 s27, s27, s31
	global_load_dword v18, v74, s[24:25]
	global_load_dword v50, v74, s[26:27]
	s_add_u32 s24, s24, s30
	s_addc_u32 s25, s25, s31
	s_add_u32 s26, s26, s30
	s_addc_u32 s27, s27, s31
	global_load_dword v19, v74, s[24:25]
	global_load_dword v51, v74, s[26:27]
	s_add_u32 s24, s24, s30
	s_addc_u32 s25, s25, s31
	s_add_u32 s26, s26, s30
	s_addc_u32 s27, s27, s31
	global_load_dword v20, v74, s[24:25]
	global_load_dword v52, v74, s[26:27]
	s_add_u32 s24, s24, s30
	s_addc_u32 s25, s25, s31
	s_add_u32 s26, s26, s30
	s_addc_u32 s27, s27, s31
	global_load_dword v21, v74, s[24:25]
	global_load_dword v53, v74, s[26:27]
	s_add_u32 s24, s24, s30
	s_addc_u32 s25, s25, s31
	s_add_u32 s26, s26, s30
	s_addc_u32 s27, s27, s31
	global_load_dword v22, v74, s[24:25]
	global_load_dword v54, v74, s[26:27]
	s_add_u32 s24, s24, s30
	s_addc_u32 s25, s25, s31
	s_add_u32 s26, s26, s30
	s_addc_u32 s27, s27, s31
	global_load_dword v23, v74, s[24:25]
	global_load_dword v55, v74, s[26:27]
	s_add_u32 s24, s24, s30
	s_addc_u32 s25, s25, s31
	s_add_u32 s26, s26, s30
	s_addc_u32 s27, s27, s31
	global_load_dword v24, v74, s[24:25]
	global_load_dword v56, v74, s[26:27]
	s_add_u32 s24, s24, s30
	s_addc_u32 s25, s25, s31
	s_add_u32 s26, s26, s30
	s_addc_u32 s27, s27, s31
	global_load_dword v25, v74, s[24:25]
	global_load_dword v57, v74, s[26:27]
	s_add_u32 s24, s24, s30
	s_addc_u32 s25, s25, s31
	s_add_u32 s26, s26, s30
	s_addc_u32 s27, s27, s31
	global_load_dword v26, v74, s[24:25]
	global_load_dword v58, v74, s[26:27]
	s_add_u32 s24, s24, s30
	s_addc_u32 s25, s25, s31
	s_add_u32 s26, s26, s30
	s_addc_u32 s27, s27, s31
	global_load_dword v27, v74, s[24:25]
	global_load_dword v59, v74, s[26:27]
	s_add_u32 s24, s24, s30
	s_addc_u32 s25, s25, s31
	s_add_u32 s26, s26, s30
	s_addc_u32 s27, s27, s31
	global_load_dword v28, v74, s[24:25]
	global_load_dword v60, v74, s[26:27]
	s_add_u32 s24, s24, s30
	s_addc_u32 s25, s25, s31
	s_add_u32 s26, s26, s30
	s_addc_u32 s27, s27, s31
	global_load_dword v29, v74, s[24:25]
	global_load_dword v61, v74, s[26:27]
	s_add_u32 s24, s24, s30
	s_addc_u32 s25, s25, s31
	s_add_u32 s26, s26, s30
	s_addc_u32 s27, s27, s31
	global_load_dword v30, v74, s[24:25]
	global_load_dword v62, v74, s[26:27]
	s_add_u32 s24, s24, s30
	s_addc_u32 s25, s25, s31
	s_add_u32 s26, s26, s30
	s_addc_u32 s27, s27, s31
	global_load_dword v31, v74, s[24:25]
	global_load_dword v63, v74, s[26:27]
	s_add_u32 s24, s24, s30
	s_addc_u32 s25, s25, s31
	s_add_u32 s26, s26, s30
	s_addc_u32 s27, s27, s31
	global_load_dword v32, v74, s[24:25]
	global_load_dword v64, v74, s[26:27]
	s_add_u32 s24, s24, s30
	s_addc_u32 s25, s25, s31
	s_add_u32 s26, s26, s30
	s_addc_u32 s27, s27, s31
	global_load_dword v33, v74, s[24:25]
	global_load_dword v65, v74, s[26:27]
	s_add_u32 s24, s24, s30
	s_addc_u32 s25, s25, s31
	s_add_u32 s26, s26, s30
	s_addc_u32 s27, s27, s31
	global_load_dword v34, v74, s[24:25]
	global_load_dword v66, v74, s[26:27]
	s_add_u32 s24, s24, s30
	s_addc_u32 s25, s25, s31
	s_add_u32 s26, s26, s30
	s_addc_u32 s27, s27, s31
	global_load_dword v35, v74, s[24:25]
	global_load_dword v67, v74, s[26:27]
	s_add_u32 s24, s24, s30
	s_addc_u32 s25, s25, s31
	s_add_u32 s26, s26, s30
	s_addc_u32 s27, s27, s31
	global_load_dword v36, v74, s[24:25]
	global_load_dword v68, v74, s[26:27]
	s_add_u32 s24, s24, s30
	s_addc_u32 s25, s25, s31
	s_add_u32 s26, s26, s30
	s_addc_u32 s27, s27, s31
	global_load_dword v37, v74, s[24:25]
	global_load_dword v69, v74, s[26:27]
	s_add_u32 s24, s24, s30
	s_addc_u32 s25, s25, s31
	s_add_u32 s26, s26, s30
	s_addc_u32 s27, s27, s31
	global_load_dword v38, v74, s[24:25]
	global_load_dword v70, v74, s[26:27]
	s_add_u32 s24, s24, s30
	s_addc_u32 s25, s25, s31
	s_add_u32 s26, s26, s30
	s_addc_u32 s27, s27, s31
	global_load_dword v39, v74, s[24:25]
	global_load_dword v71, v74, s[26:27]
	v_mov_b32_e32 v72, 0
	v_mov_b32_e32 v73, 1.0
	s_waitcnt vmcnt(0)
	v_fma_f32 v72, v8, v72, v40
	v_mul_f32_e32 v73, v73, v8
	v_fma_f32 v72, v9, v72, v41
	v_mul_f32_e32 v73, v73, v9
	v_fma_f32 v72, v10, v72, v42
	v_mul_f32_e32 v73, v73, v10
	v_fma_f32 v72, v11, v72, v43
	v_mul_f32_e32 v73, v73, v11
	v_fma_f32 v72, v12, v72, v44
	v_mul_f32_e32 v73, v73, v12
	v_fma_f32 v72, v13, v72, v45
	v_mul_f32_e32 v73, v73, v13
	v_fma_f32 v72, v14, v72, v46
	v_mul_f32_e32 v73, v73, v14
	v_fma_f32 v72, v15, v72, v47
	v_mul_f32_e32 v73, v73, v15
	v_fma_f32 v72, v16, v72, v48
	v_mul_f32_e32 v73, v73, v16
	v_fma_f32 v72, v17, v72, v49
	v_mul_f32_e32 v73, v73, v17
	v_fma_f32 v72, v18, v72, v50
	v_mul_f32_e32 v73, v73, v18
	v_fma_f32 v72, v19, v72, v51
	v_mul_f32_e32 v73, v73, v19
	v_fma_f32 v72, v20, v72, v52
	v_mul_f32_e32 v73, v73, v20
	v_fma_f32 v72, v21, v72, v53
	v_mul_f32_e32 v73, v73, v21
	v_fma_f32 v72, v22, v72, v54
	v_mul_f32_e32 v73, v73, v22
	v_fma_f32 v72, v23, v72, v55
	v_mul_f32_e32 v73, v73, v23
	v_fma_f32 v72, v24, v72, v56
	v_mul_f32_e32 v73, v73, v24
	v_fma_f32 v72, v25, v72, v57
	v_mul_f32_e32 v73, v73, v25
	v_fma_f32 v72, v26, v72, v58
	v_mul_f32_e32 v73, v73, v26
	v_fma_f32 v72, v27, v72, v59
	v_mul_f32_e32 v73, v73, v27
	v_fma_f32 v72, v28, v72, v60
	v_mul_f32_e32 v73, v73, v28
	v_fma_f32 v72, v29, v72, v61
	v_mul_f32_e32 v73, v73, v29
	v_fma_f32 v72, v30, v72, v62
	v_mul_f32_e32 v73, v73, v30
	v_fma_f32 v72, v31, v72, v63
	v_mul_f32_e32 v73, v73, v31
	v_fma_f32 v72, v32, v72, v64
	v_mul_f32_e32 v73, v73, v32
	v_fma_f32 v72, v33, v72, v65
	v_mul_f32_e32 v73, v73, v33
	v_fma_f32 v72, v34, v72, v66
	v_mul_f32_e32 v73, v73, v34
	v_fma_f32 v72, v35, v72, v67
	v_mul_f32_e32 v73, v73, v35
	v_fma_f32 v72, v36, v72, v68
	v_mul_f32_e32 v73, v73, v36
	v_fma_f32 v72, v37, v72, v69
	v_mul_f32_e32 v73, v73, v37
	v_fma_f32 v72, v38, v72, v70
	v_mul_f32_e32 v73, v73, v38
	v_fma_f32 v72, v39, v72, v71
	v_mul_f32_e32 v73, v73, v39
	v_add_u32_e32 v78, 56, v0
	v_and_b32_e32 v78, 63, v78
	v_lshlrev_b32_e32 v78, 2, v78
	ds_bpermute_b32 v79, v78, v72
	ds_bpermute_b32 v80, v78, v73
	v_cmp_lt_u32_e32 vcc, 7, v0
	s_waitcnt lgkmcnt(0)
; __device__ __forceinline__ int obid() { int t = blockIdx.x; asm volatile("" : "+s"(t)); return t; }
; __device__ void phase_scan(const Params& p) {
;     ...
;         const float* __restrict__ Aprod = (const float*)(ws + WS_AP); const float* __restrict__ Hend = (const float*)(ws + WS_HE); float* __restrict__ carry = (float*)(ws + WS_CA);
;         const int gid = obid() * 128 + (tid - 256); const int dir = gid >> 9, ch = gid & 511;
;         float hc = 0.f;
;         const long step = dir ? -1 : 1; const size_t base = (size_t)(dir * NCH + (dir ? NCH - 1 : 0)) * 512 + ch;
; #pragma unroll 1
;         for (int st = 0; st < NCH; st += 64) {
;             float ab[64], hb[64];
; #pragma unroll
;             for (int i = 0; i < 64; ++i) { ab[i] = Aprod[base + (long)(st + i) * step * 512]; hb[i] = Hend[base + (long)(st + i) * step * 512]; }
; #pragma unroll
;             for (int i = 0; i < 64; ++i) { carry[base + (long)(st + i) * step * 512] = hc; hc = ab[i] * hc + hb[i]; }
;         }
	v_fma_f32 v81, v73, v79, v72
	v_mul_f32_e32 v82, v73, v80
	s_nop 0
	v_cndmask_b32_e32 v72, v72, v81, vcc
	v_cndmask_b32_e32 v73, v73, v82, vcc
	s_nop 0
	v_add_u32_e32 v78, 48, v0
	v_and_b32_e32 v78, 63, v78
	v_lshlrev_b32_e32 v78, 2, v78
	ds_bpermute_b32 v79, v78, v72
	ds_bpermute_b32 v80, v78, v73
	v_cmp_lt_u32_e32 vcc, 15, v0
	s_waitcnt lgkmcnt(0)
	v_fma_f32 v81, v73, v79, v72
	v_mul_f32_e32 v82, v73, v80
	s_nop 0
	v_cndmask_b32_e32 v72, v72, v81, vcc
	v_cndmask_b32_e32 v73, v73, v82, vcc
	s_nop 0
	v_add_u32_e32 v78, 32, v0
	v_and_b32_e32 v78, 63, v78
	v_lshlrev_b32_e32 v78, 2, v78
	ds_bpermute_b32 v79, v78, v72
	ds_bpermute_b32 v80, v78, v73
	v_cmp_lt_u32_e32 vcc, 31, v0
	s_waitcnt lgkmcnt(0)
	v_fma_f32 v81, v73, v79, v72
	v_mul_f32_e32 v82, v73, v80
	s_nop 0
	v_cndmask_b32_e32 v72, v72, v81, vcc
	v_cndmask_b32_e32 v73, v73, v82, vcc
	s_nop 0
	v_add_u32_e32 v78, 56, v0
	v_and_b32_e32 v78, 63, v78
	v_lshlrev_b32_e32 v78, 2, v78
	ds_bpermute_b32 v79, v78, v72
	v_cmp_lt_u32_e32 vcc, 7, v0
	s_nop 1
	s_waitcnt lgkmcnt(0)
	v_cndmask_b32_e32 v72, 0, v79, vcc
	v_mov_b32_e32 v83, v72
	global_store_dword v74, v83, s[28:29]
	v_fma_f32 v72, v8, v72, v40
	s_add_u32 s28, s28, s30
	s_addc_u32 s29, s29, s31
	v_mov_b32_e32 v84, v72
	global_store_dword v74, v84, s[28:29]
	v_fma_f32 v72, v9, v72, v41
	s_add_u32 s28, s28, s30
	s_addc_u32 s29, s29, s31
	v_mov_b32_e32 v83, v72
	global_store_dword v74, v83, s[28:29]
	v_fma_f32 v72, v10, v72, v42
	s_add_u32 s28, s28, s30
	s_addc_u32 s29, s29, s31
	v_mov_b32_e32 v84, v72
	global_store_dword v74, v84, s[28:29]
	v_fma_f32 v72, v11, v72, v43
	s_add_u32 s28, s28, s30
	s_addc_u32 s29, s29, s31
	v_mov_b32_e32 v83, v72
	global_store_dword v74, v83, s[28:29]
	v_fma_f32 v72, v12, v72, v44
	s_add_u32 s28, s28, s30
	s_addc_u32 s29, s29, s31
	v_mov_b32_e32 v84, v72
	global_store_dword v74, v84, s[28:29]
	v_fma_f32 v72, v13, v72, v45
	s_add_u32 s28, s28, s30
	s_addc_u32 s29, s29, s31
	v_mov_b32_e32 v83, v72
	global_store_dword v74, v83, s[28:29]
	v_fma_f32 v72, v14, v72, v46
	s_add_u32 s28, s28, s30
	s_addc_u32 s29, s29, s31
	v_mov_b32_e32 v84, v72
	global_store_dword v74, v84, s[28:29]
	v_fma_f32 v72, v15, v72, v47
	s_add_u32 s28, s28, s30
	s_addc_u32 s29, s29, s31
	v_mov_b32_e32 v83, v72
	global_store_dword v74, v83, s[28:29]
	v_fma_f32 v72, v16, v72, v48
	s_add_u32 s28, s28, s30
	s_addc_u32 s29, s29, s31
	v_mov_b32_e32 v84, v72
	global_store_dword v74, v84, s[28:29]
	v_fma_f32 v72, v17, v72, v49
	s_add_u32 s28, s28, s30
	s_addc_u32 s29, s29, s31
	v_mov_b32_e32 v83, v72
	global_store_dword v74, v83, s[28:29]
	v_fma_f32 v72, v18, v72, v50
	s_add_u32 s28, s28, s30
	s_addc_u32 s29, s29, s31
	v_mov_b32_e32 v84, v72
	global_store_dword v74, v84, s[28:29]
	v_fma_f32 v72, v19, v72, v51
	s_add_u32 s28, s28, s30
	s_addc_u32 s29, s29, s31
	v_mov_b32_e32 v83, v72
	global_store_dword v74, v83, s[28:29]
	v_fma_f32 v72, v20, v72, v52
	s_add_u32 s28, s28, s30
	s_addc_u32 s29, s29, s31
	v_mov_b32_e32 v84, v72
	global_store_dword v74, v84, s[28:29]
	v_fma_f32 v72, v21, v72, v53
	s_add_u32 s28, s28, s30
	s_addc_u32 s29, s29, s31
	v_mov_b32_e32 v83, v72
	global_store_dword v74, v83, s[28:29]
	v_fma_f32 v72, v22, v72, v54
	s_add_u32 s28, s28, s30
	s_addc_u32 s29, s29, s31
	v_mov_b32_e32 v84, v72
	global_store_dword v74, v84, s[28:29]
	v_fma_f32 v72, v23, v72, v55
	s_add_u32 s28, s28, s30
	s_addc_u32 s29, s29, s31
	v_mov_b32_e32 v83, v72
	global_store_dword v74, v83, s[28:29]
	v_fma_f32 v72, v24, v72, v56
	s_add_u32 s28, s28, s30
	s_addc_u32 s29, s29, s31
	v_mov_b32_e32 v84, v72
	global_store_dword v74, v84, s[28:29]
	v_fma_f32 v72, v25, v72, v57
	s_add_u32 s28, s28, s30
	s_addc_u32 s29, s29, s31
	v_mov_b32_e32 v83, v72
	global_store_dword v74, v83, s[28:29]
	v_fma_f32 v72, v26, v72, v58
	s_add_u32 s28, s28, s30
	s_addc_u32 s29, s29, s31
	v_mov_b32_e32 v84, v72
	global_store_dword v74, v84, s[28:29]
	v_fma_f32 v72, v27, v72, v59
	s_add_u32 s28, s28, s30
	s_addc_u32 s29, s29, s31
	v_mov_b32_e32 v83, v72
	global_store_dword v74, v83, s[28:29]
	v_fma_f32 v72, v28, v72, v60
	s_add_u32 s28, s28, s30
	s_addc_u32 s29, s29, s31
	v_mov_b32_e32 v84, v72
	global_store_dword v74, v84, s[28:29]
	v_fma_f32 v72, v29, v72, v61
	s_add_u32 s28, s28, s30
	s_addc_u32 s29, s29, s31
	v_mov_b32_e32 v83, v72
	global_store_dword v74, v83, s[28:29]
	v_fma_f32 v72, v30, v72, v62
	s_add_u32 s28, s28, s30
	s_addc_u32 s29, s29, s31
	v_mov_b32_e32 v84, v72
	global_store_dword v74, v84, s[28:29]
	v_fma_f32 v72, v31, v72, v63
	s_add_u32 s28, s28, s30
	s_addc_u32 s29, s29, s31
	v_mov_b32_e32 v83, v72
	global_store_dword v74, v83, s[28:29]
	v_fma_f32 v72, v32, v72, v64
	s_add_u32 s28, s28, s30
	s_addc_u32 s29, s29, s31
	v_mov_b32_e32 v84, v72
	global_store_dword v74, v84, s[28:29]
	v_fma_f32 v72, v33, v72, v65
	s_add_u32 s28, s28, s30
	s_addc_u32 s29, s29, s31
	v_mov_b32_e32 v83, v72
	global_store_dword v74, v83, s[28:29]
	v_fma_f32 v72, v34, v72, v66
	s_add_u32 s28, s28, s30
	s_addc_u32 s29, s29, s31
	v_mov_b32_e32 v84, v72
	global_store_dword v74, v84, s[28:29]
	v_fma_f32 v72, v35, v72, v67
	s_add_u32 s28, s28, s30
	s_addc_u32 s29, s29, s31
	v_mov_b32_e32 v83, v72
	global_store_dword v74, v83, s[28:29]
	v_fma_f32 v72, v36, v72, v68
	s_add_u32 s28, s28, s30
	s_addc_u32 s29, s29, s31
	v_mov_b32_e32 v84, v72
	global_store_dword v74, v84, s[28:29]
	v_fma_f32 v72, v37, v72, v69
	s_add_u32 s28, s28, s30
	s_addc_u32 s29, s29, s31
	v_mov_b32_e32 v83, v72
	global_store_dword v74, v83, s[28:29]
	v_fma_f32 v72, v38, v72, v70
	s_add_u32 s28, s28, s30
	s_addc_u32 s29, s29, s31
	v_mov_b32_e32 v84, v72
	global_store_dword v74, v84, s[28:29]
	v_fma_f32 v72, v39, v72, v71
; __device__ __forceinline__ int obid() { int t = blockIdx.x; asm volatile("" : "+s"(t)); return t; }
; __device__ void phase_scan(const Params& p) {
;     ...
;         const bf16_t* __restrict__ uT = (const bf16_t*)(ws + WS_M); bf16_t* __restrict__ spT = (bf16_t*)(ws + WS_M + (size_t)S * D * 2); const float* __restrict__ dec = (const float*)(ws + WS_DEC);
;         for (int gid = obid() * 256 + tid; gid < 65536; gid += gridDim.x * 256) {
;             const int dir = gid >> 15, rem = gid & 32767, h = rem >> 13, vd = rem & 8191, d = vd & 63;
;             float s = 0.f;
;             const long step = dir ? -1 : 1; const int nfirst = dir ? NCH - 1 : 0;
;             const bf16_t* up = uT + ((size_t)(dir * NCH + nfirst) * 4 + h) * 8192 + vd; bf16_t* sp = spT + ((size_t)(dir * NCH + nfirst) * 4 + h) * 8192 + vd;
;             const float* dp = dec + ((size_t)(dir * NCH + nfirst) * 4 + h) * 64 + d;
; #pragma unroll 1
;             for (int st = 0; st < NCH; st += 64) {
;                 bf16_t ub[64]; float db[64];
; #pragma unroll
;                 for (int i = 0; i < 64; ++i) { ub[i] = up[(long)(st + i) * step * 32768]; db[i] = dp[(long)(st + i) * step * 256]; }
	global_load_ushort v8, v1, s[16:17]
	s_add_u32 s16, s16, s20
	s_addc_u32 s17, s17, s21
	global_load_ushort v9, v1, s[16:17]
	s_add_u32 s16, s16, s20
	s_addc_u32 s17, s17, s21
	global_load_ushort v10, v1, s[16:17]
	s_add_u32 s16, s16, s20
	s_addc_u32 s17, s17, s21
	global_load_ushort v11, v1, s[16:17]
	s_add_u32 s16, s16, s20
	s_addc_u32 s17, s17, s21
	global_load_ushort v12, v1, s[16:17]
	s_add_u32 s16, s16, s20
	s_addc_u32 s17, s17, s21
	global_load_ushort v13, v1, s[16:17]
	s_add_u32 s16, s16, s20
	s_addc_u32 s17, s17, s21
	global_load_ushort v14, v1, s[16:17]
	s_add_u32 s16, s16, s20
	s_addc_u32 s17, s17, s21
	global_load_ushort v15, v1, s[16:17]
	s_add_u32 s16, s16, s20
	s_addc_u32 s17, s17, s21
	global_load_ushort v16, v1, s[16:17]
	s_add_u32 s16, s16, s20
	s_addc_u32 s17, s17, s21
	global_load_ushort v17, v1, s[16:17]
	s_add_u32 s16, s16, s20
	s_addc_u32 s17, s17, s21
	global_load_ushort v18, v1, s[16:17]
	s_add_u32 s16, s16, s20
	s_addc_u32 s17, s17, s21
	global_load_ushort v19, v1, s[16:17]
	s_add_u32 s16, s16, s20
	s_addc_u32 s17, s17, s21
	global_load_ushort v20, v1, s[16:17]
	s_add_u32 s16, s16, s20
	s_addc_u32 s17, s17, s21
	global_load_ushort v21, v1, s[16:17]
	s_add_u32 s16, s16, s20
	s_addc_u32 s17, s17, s21
	global_load_ushort v22, v1, s[16:17]
	s_add_u32 s16, s16, s20
	s_addc_u32 s17, s17, s21
	global_load_ushort v23, v1, s[16:17]
	s_add_u32 s16, s16, s20
	s_addc_u32 s17, s17, s21
	global_load_ushort v24, v1, s[16:17]
	s_add_u32 s16, s16, s20
	s_addc_u32 s17, s17, s21
	global_load_ushort v25, v1, s[16:17]
	s_add_u32 s16, s16, s20
	s_addc_u32 s17, s17, s21
	global_load_ushort v26, v1, s[16:17]
	s_add_u32 s16, s16, s20
	s_addc_u32 s17, s17, s21
	global_load_ushort v27, v1, s[16:17]
	s_add_u32 s16, s16, s20
	s_addc_u32 s17, s17, s21
	global_load_ushort v28, v1, s[16:17]
	s_add_u32 s16, s16, s20
	s_addc_u32 s17, s17, s21
	global_load_ushort v29, v1, s[16:17]
	s_add_u32 s16, s16, s20
	s_addc_u32 s17, s17, s21
	global_load_ushort v30, v1, s[16:17]
	s_add_u32 s16, s16, s20
	s_addc_u32 s17, s17, s21
	global_load_ushort v31, v1, s[16:17]
	s_add_u32 s16, s16, s20
	s_addc_u32 s17, s17, s21
	global_load_ushort v32, v1, s[16:17]
	s_add_u32 s16, s16, s20
	s_addc_u32 s17, s17, s21
	global_load_ushort v33, v1, s[16:17]
	s_add_u32 s16, s16, s20
	s_addc_u32 s17, s17, s21
	global_load_ushort v34, v1, s[16:17]
	s_add_u32 s16, s16, s20
	s_addc_u32 s17, s17, s21
	global_load_ushort v35, v1, s[16:17]
	s_add_u32 s16, s16, s20
	s_addc_u32 s17, s17, s21
	global_load_ushort v36, v1, s[16:17]
	s_add_u32 s16, s16, s20
	s_addc_u32 s17, s17, s21
	global_load_ushort v37, v1, s[16:17]
	s_add_u32 s16, s16, s20
	s_addc_u32 s17, s17, s21
	global_load_ushort v38, v1, s[16:17]
	s_add_u32 s16, s16, s20
	s_addc_u32 s17, s17, s21
	global_load_ushort v39, v1, s[16:17]
	s_add_u32 s16, s16, s20
	s_addc_u32 s17, s17, s21
	global_load_ushort v40, v1, s[16:17]
	s_add_u32 s16, s16, s20
	s_addc_u32 s17, s17, s21
	global_load_ushort v41, v1, s[16:17]
	s_add_u32 s16, s16, s20
	s_addc_u32 s17, s17, s21
	global_load_ushort v42, v1, s[16:17]
	s_add_u32 s16, s16, s20
	s_addc_u32 s17, s17, s21
	global_load_ushort v43, v1, s[16:17]
	s_add_u32 s16, s16, s20
	s_addc_u32 s17, s17, s21
	global_load_ushort v44, v1, s[16:17]
	s_add_u32 s16, s16, s20
	s_addc_u32 s17, s17, s21
	global_load_ushort v45, v1, s[16:17]
	s_add_u32 s16, s16, s20
	s_addc_u32 s17, s17, s21
	global_load_ushort v46, v1, s[16:17]
	s_add_u32 s16, s16, s20
	s_addc_u32 s17, s17, s21
	global_load_ushort v47, v1, s[16:17]
	s_add_u32 s16, s16, s20
	s_addc_u32 s17, s17, s21
	global_load_ushort v48, v1, s[16:17]
	s_add_u32 s16, s16, s20
	s_addc_u32 s17, s17, s21
	global_load_ushort v49, v1, s[16:17]
	s_add_u32 s16, s16, s20
	s_addc_u32 s17, s17, s21
	global_load_ushort v50, v1, s[16:17]
	s_add_u32 s16, s16, s20
	s_addc_u32 s17, s17, s21
	global_load_ushort v51, v1, s[16:17]
	s_add_u32 s16, s16, s20
	s_addc_u32 s17, s17, s21
	global_load_ushort v52, v1, s[16:17]
	s_add_u32 s16, s16, s20
	s_addc_u32 s17, s17, s21
	global_load_ushort v53, v1, s[16:17]
	s_add_u32 s16, s16, s20
	s_addc_u32 s17, s17, s21
	global_load_ushort v54, v1, s[16:17]
	s_add_u32 s16, s16, s20
	s_addc_u32 s17, s17, s21
	global_load_ushort v55, v1, s[16:17]
	s_add_u32 s16, s16, s20
	s_addc_u32 s17, s17, s21
	global_load_ushort v56, v1, s[16:17]
	s_add_u32 s16, s16, s20
	s_addc_u32 s17, s17, s21
	global_load_ushort v57, v1, s[16:17]
	s_add_u32 s16, s16, s20
	s_addc_u32 s17, s17, s21
	global_load_ushort v58, v1, s[16:17]
	s_add_u32 s16, s16, s20
	s_addc_u32 s17, s17, s21
	global_load_ushort v59, v1, s[16:17]
	s_add_u32 s16, s16, s20
	s_addc_u32 s17, s17, s21
	global_load_ushort v60, v1, s[16:17]
	s_add_u32 s16, s16, s20
	s_addc_u32 s17, s17, s21
	global_load_ushort v61, v1, s[16:17]
	s_add_u32 s16, s16, s20
	s_addc_u32 s17, s17, s21
	global_load_ushort v62, v1, s[16:17]
	s_add_u32 s16, s16, s20
	s_addc_u32 s17, s17, s21
	global_load_ushort v63, v1, s[16:17]
	s_add_u32 s16, s16, s20
	s_addc_u32 s17, s17, s21
	global_load_ushort v64, v1, s[16:17]
	s_add_u32 s16, s16, s20
	s_addc_u32 s17, s17, s21
	global_load_ushort v65, v1, s[16:17]
	s_add_u32 s16, s16, s20
	s_addc_u32 s17, s17, s21
	global_load_ushort v66, v1, s[16:17]
	s_add_u32 s16, s16, s20
	s_addc_u32 s17, s17, s21
	global_load_ushort v67, v1, s[16:17]
	s_add_u32 s16, s16, s20
	s_addc_u32 s17, s17, s21
	global_load_ushort v68, v1, s[16:17]
	s_add_u32 s16, s16, s20
	s_addc_u32 s17, s17, s21
	global_load_ushort v69, v1, s[16:17]
	s_add_u32 s16, s16, s20
	s_addc_u32 s17, s17, s21
	global_load_ushort v70, v1, s[16:17]
	s_add_u32 s16, s16, s20
	s_addc_u32 s17, s17, s21
	global_load_ushort v71, v1, s[16:17]
; __device__ __forceinline__ int obid() { int t = blockIdx.x; asm volatile("" : "+s"(t)); return t; }
; __device__ void phase_scan(const Params& p) {
;     ...
;         const bf16_t* __restrict__ uT = (const bf16_t*)(ws + WS_M); bf16_t* __restrict__ spT = (bf16_t*)(ws + WS_M + (size_t)S * D * 2); const float* __restrict__ dec = (const float*)(ws + WS_DEC);
;         for (int gid = obid() * 256 + tid; gid < 65536; gid += gridDim.x * 256) {
;             const int dir = gid >> 15, rem = gid & 32767, h = rem >> 13, vd = rem & 8191, d = vd & 63;
;             float s = 0.f;
;             const long step = dir ? -1 : 1; const int nfirst = dir ? NCH - 1 : 0;
;             const bf16_t* up = uT + ((size_t)(dir * NCH + nfirst) * 4 + h) * 8192 + vd; bf16_t* sp = spT + ((size_t)(dir * NCH + nfirst) * 4 + h) * 8192 + vd;
;             const float* dp = dec + ((size_t)(dir * NCH + nfirst) * 4 + h) * 64 + d;
; #pragma unroll 1
;             for (int st = 0; st < NCH; st += 64) {
;                 bf16_t ub[64]; float db[64];
; #pragma unroll
;                 for (int i = 0; i < 64; ++i) { ub[i] = up[(long)(st + i) * step * 32768]; db[i] = dp[(long)(st + i) * step * 256]; }
	s_add_u32 s16, s16, s20
	s_addc_u32 s17, s17, s21
	global_load_ushort v72, v1, s[16:17]
	s_add_u32 s16, s16, s20
	s_addc_u32 s17, s17, s21
	global_load_ushort v73, v1, s[16:17]
	s_add_u32 s16, s16, s20
	s_addc_u32 s17, s17, s21
	global_load_ushort v74, v1, s[16:17]
	s_add_u32 s16, s16, s20
	s_addc_u32 s17, s17, s21
	global_load_ushort v75, v1, s[16:17]
	s_add_u32 s16, s16, s20
	s_addc_u32 s17, s17, s21
	global_load_ushort v76, v1, s[16:17]
	s_add_u32 s16, s16, s20
	s_addc_u32 s17, s17, s21
	global_load_ushort v77, v1, s[16:17]
	s_add_u32 s16, s16, s20
	s_addc_u32 s17, s17, s21
	global_load_ushort v78, v1, s[16:17]
	s_add_u32 s16, s16, s20
	s_addc_u32 s17, s17, s21
	global_load_ushort v79, v1, s[16:17]
	s_add_u32 s16, s16, s20
	s_addc_u32 s17, s17, s21
	global_load_ushort v80, v1, s[16:17]
	s_add_u32 s16, s16, s20
	s_addc_u32 s17, s17, s21
	global_load_ushort v81, v1, s[16:17]
	s_add_u32 s16, s16, s20
	s_addc_u32 s17, s17, s21
	global_load_ushort v82, v1, s[16:17]
	s_add_u32 s16, s16, s20
	s_addc_u32 s17, s17, s21
	global_load_ushort v83, v1, s[16:17]
	s_add_u32 s16, s16, s20
	s_addc_u32 s17, s17, s21
	global_load_ushort v84, v1, s[16:17]
	s_add_u32 s16, s16, s20
	s_addc_u32 s17, s17, s21
	global_load_ushort v85, v1, s[16:17]
	s_add_u32 s16, s16, s20
	s_addc_u32 s17, s17, s21
	global_load_ushort v86, v1, s[16:17]
	s_add_u32 s16, s16, s20
	s_addc_u32 s17, s17, s21
	global_load_ushort v87, v1, s[16:17]
	s_add_u32 s16, s16, s20
	s_addc_u32 s17, s17, s21
	global_load_ushort v88, v1, s[16:17]
	s_add_u32 s16, s16, s20
	s_addc_u32 s17, s17, s21
	global_load_ushort v89, v1, s[16:17]
	s_add_u32 s16, s16, s20
	s_addc_u32 s17, s17, s21
	global_load_ushort v90, v1, s[16:17]
	s_add_u32 s16, s16, s20
	s_addc_u32 s17, s17, s21
	global_load_ushort v91, v1, s[16:17]
	s_add_u32 s16, s16, s20
	s_addc_u32 s17, s17, s21
	global_load_ushort v92, v1, s[16:17]
	s_add_u32 s16, s16, s20
	s_addc_u32 s17, s17, s21
	global_load_ushort v93, v1, s[16:17]
	s_add_u32 s16, s16, s20
	s_addc_u32 s17, s17, s21
	global_load_ushort v94, v1, s[16:17]
	s_add_u32 s16, s16, s20
	s_addc_u32 s17, s17, s21
	global_load_ushort v95, v1, s[16:17]
	s_add_u32 s16, s16, s20
	s_addc_u32 s17, s17, s21
	global_load_ushort v96, v1, s[16:17]
	s_add_u32 s16, s16, s20
	s_addc_u32 s17, s17, s21
	global_load_ushort v97, v1, s[16:17]
	s_add_u32 s16, s16, s20
	s_addc_u32 s17, s17, s21
	global_load_ushort v98, v1, s[16:17]
	s_add_u32 s16, s16, s20
	s_addc_u32 s17, s17, s21
	global_load_ushort v99, v1, s[16:17]
	s_add_u32 s16, s16, s20
	s_addc_u32 s17, s17, s21
	global_load_ushort v100, v1, s[16:17]
	s_add_u32 s16, s16, s20
	s_addc_u32 s17, s17, s21
	global_load_ushort v101, v1, s[16:17]
	s_add_u32 s16, s16, s20
	s_addc_u32 s17, s17, s21
	global_load_ushort v102, v1, s[16:17]
	s_add_u32 s16, s16, s20
	s_addc_u32 s17, s17, s21
	global_load_ushort v103, v1, s[16:17]
	s_add_u32 s16, s16, s20
	s_addc_u32 s17, s17, s21
	global_load_ushort v104, v1, s[16:17]
	s_add_u32 s16, s16, s20
	s_addc_u32 s17, s17, s21
	global_load_ushort v105, v1, s[16:17]
	s_add_u32 s16, s16, s20
	s_addc_u32 s17, s17, s21
	global_load_ushort v106, v1, s[16:17]
	s_add_u32 s16, s16, s20
	s_addc_u32 s17, s17, s21
	global_load_ushort v107, v1, s[16:17]
	s_add_u32 s16, s16, s20
	s_addc_u32 s17, s17, s21
	global_load_ushort v108, v1, s[16:17]
	s_add_u32 s16, s16, s20
	s_addc_u32 s17, s17, s21
	global_load_ushort v109, v1, s[16:17]
	s_add_u32 s16, s16, s20
	s_addc_u32 s17, s17, s21
	global_load_ushort v110, v1, s[16:17]
	s_add_u32 s16, s16, s20
	s_addc_u32 s17, s17, s21
	global_load_ushort v111, v1, s[16:17]
	s_add_u32 s16, s16, s20
	s_addc_u32 s17, s17, s21
	global_load_ushort v112, v1, s[16:17]
	s_add_u32 s16, s16, s20
	s_addc_u32 s17, s17, s21
	global_load_ushort v113, v1, s[16:17]
	s_add_u32 s16, s16, s20
	s_addc_u32 s17, s17, s21
	global_load_ushort v114, v1, s[16:17]
	s_add_u32 s16, s16, s20
	s_addc_u32 s17, s17, s21
	global_load_ushort v115, v1, s[16:17]
	s_add_u32 s16, s16, s20
	s_addc_u32 s17, s17, s21
	global_load_ushort v116, v1, s[16:17]
	s_add_u32 s16, s16, s20
	s_addc_u32 s17, s17, s21
	global_load_ushort v117, v1, s[16:17]
	s_add_u32 s16, s16, s20
	s_addc_u32 s17, s17, s21
	global_load_ushort v118, v1, s[16:17]
	s_add_u32 s16, s16, s20
	s_addc_u32 s17, s17, s21
	global_load_ushort v119, v1, s[16:17]
	s_add_u32 s16, s16, s20
	s_addc_u32 s17, s17, s21
	global_load_ushort v120, v1, s[16:17]
	s_add_u32 s16, s16, s20
	s_addc_u32 s17, s17, s21
	global_load_ushort v121, v1, s[16:17]
	s_add_u32 s16, s16, s20
	s_addc_u32 s17, s17, s21
	global_load_ushort v122, v1, s[16:17]
	s_add_u32 s16, s16, s20
	s_addc_u32 s17, s17, s21
	global_load_ushort v123, v1, s[16:17]
	s_add_u32 s16, s16, s20
	s_addc_u32 s17, s17, s21
	global_load_ushort v124, v1, s[16:17]
	s_add_u32 s16, s16, s20
	s_addc_u32 s17, s17, s21
	global_load_ushort v125, v1, s[16:17]
	s_add_u32 s16, s16, s20
	s_addc_u32 s17, s17, s21
	global_load_ushort v126, v1, s[16:17]
	s_add_u32 s16, s16, s20
	s_addc_u32 s17, s17, s21
	global_load_ushort v127, v1, s[16:17]
	s_add_u32 s16, s16, s20
	s_addc_u32 s17, s17, s21
	global_load_ushort v128, v1, s[16:17]
	s_add_u32 s16, s16, s20
	s_addc_u32 s17, s17, s21
	global_load_ushort v129, v1, s[16:17]
	s_add_u32 s16, s16, s20
	s_addc_u32 s17, s17, s21
	global_load_ushort v130, v1, s[16:17]
	s_add_u32 s16, s16, s20
	s_addc_u32 s17, s17, s21
	global_load_ushort v131, v1, s[16:17]
	s_add_u32 s16, s16, s20
	s_addc_u32 s17, s17, s21
	global_load_ushort v132, v1, s[16:17]
	s_add_u32 s16, s16, s20
	s_addc_u32 s17, s17, s21
	global_load_ushort v133, v1, s[16:17]
	s_add_u32 s16, s16, s20
	s_addc_u32 s17, s17, s21
	global_load_ushort v134, v1, s[16:17]
	s_add_u32 s16, s16, s20
	s_addc_u32 s17, s17, s21
	global_load_ushort v135, v1, s[16:17]
; __device__ __forceinline__ float bf2f(bf16_t b) { return __uint_as_float(((unsigned)b) << 16); }
; __device__ __forceinline__ bf16_t f2bf(float f) { unsigned u = __float_as_uint(f); return (bf16_t)((u + 0x7fffu + ((u >> 16) & 1u)) >> 16); }
; __device__ void phase_scan(const Params& p) {
;     ...
; #pragma unroll 1
;             for (int st = 0; st < NCH; st += 64) {
;                 bf16_t ub[64]; float db[64];
; #pragma unroll
;                 for (int i = 0; i < 64; ++i) { ub[i] = up[(long)(st + i) * step * 32768]; db[i] = dp[(long)(st + i) * step * 256]; }
; #pragma unroll
;                 for (int i = 0; i < 64; ++i) { sp[(long)(st + i) * step * 32768] = f2bf(s); s = db[i] * s + bf2f(ub[i]); }
;             }
.Lscan_second:
	s_waitcnt vmcnt(0)
	s_barrier
	ds_read_b32 v3, v7
.Lscan_steps:
	ds_read_b32 v148, v2 offset:0
	ds_read_b32 v149, v2 offset:256
	ds_read_b32 v150, v2 offset:512
	ds_read_b32 v151, v2 offset:768
	ds_read_b32 v152, v2 offset:1024
	ds_read_b32 v153, v2 offset:1280
	ds_read_b32 v154, v2 offset:1536
	ds_read_b32 v155, v2 offset:1792
	ds_read_b32 v156, v2 offset:2048
	ds_read_b32 v157, v2 offset:2304
	ds_read_b32 v158, v2 offset:2560
	ds_read_b32 v159, v2 offset:2816
	s_waitcnt vmcnt(63)
	s_waitcnt lgkmcnt(0)
	ds_read_b32 v160, v2 offset:3072
	ds_read_b32 v161, v2 offset:3328
	ds_read_b32 v162, v2 offset:3584
	ds_read_b32 v163, v2 offset:3840
	ds_read_b32 v164, v2 offset:4096
	ds_read_b32 v165, v2 offset:4352
	ds_read_b32 v166, v2 offset:4608
	ds_read_b32 v167, v2 offset:4864
	ds_read_b32 v168, v2 offset:5120
	ds_read_b32 v169, v2 offset:5376
	ds_read_b32 v170, v2 offset:5632
	ds_read_b32 v171, v2 offset:5888
	v_cvt_pk_bf16_f32 v4, v3, v3
	global_store_short v1, v4, s[18:19]
	s_add_u32 s18, s18, s20
	s_addc_u32 s19, s19, s21
	v_lshlrev_b32_e32 v6, 16, v8
	v_fma_f32 v3, v148, v3, v6
	v_cvt_pk_bf16_f32 v5, v3, v3
	global_store_short v1, v5, s[18:19]
	s_add_u32 s18, s18, s20
	s_addc_u32 s19, s19, s21
	v_lshlrev_b32_e32 v6, 16, v9
	v_fma_f32 v3, v149, v3, v6
	v_cvt_pk_bf16_f32 v4, v3, v3
	global_store_short v1, v4, s[18:19]
	s_add_u32 s18, s18, s20
	s_addc_u32 s19, s19, s21
	v_lshlrev_b32_e32 v6, 16, v10
	v_fma_f32 v3, v150, v3, v6
	v_cvt_pk_bf16_f32 v5, v3, v3
	global_store_short v1, v5, s[18:19]
	s_add_u32 s18, s18, s20
	s_addc_u32 s19, s19, s21
	v_lshlrev_b32_e32 v6, 16, v11
	v_fma_f32 v3, v151, v3, v6
	v_cvt_pk_bf16_f32 v4, v3, v3
	global_store_short v1, v4, s[18:19]
	s_add_u32 s18, s18, s20
	s_addc_u32 s19, s19, s21
	v_lshlrev_b32_e32 v6, 16, v12
	v_fma_f32 v3, v152, v3, v6
	v_cvt_pk_bf16_f32 v5, v3, v3
	global_store_short v1, v5, s[18:19]
	s_add_u32 s18, s18, s20
	s_addc_u32 s19, s19, s21
	v_lshlrev_b32_e32 v6, 16, v13
	v_fma_f32 v3, v153, v3, v6
	v_cvt_pk_bf16_f32 v4, v3, v3
	global_store_short v1, v4, s[18:19]
	s_add_u32 s18, s18, s20
	s_addc_u32 s19, s19, s21
	v_lshlrev_b32_e32 v6, 16, v14
	v_fma_f32 v3, v154, v3, v6
	v_cvt_pk_bf16_f32 v5, v3, v3
	global_store_short v1, v5, s[18:19]
	s_add_u32 s18, s18, s20
	s_addc_u32 s19, s19, s21
	v_lshlrev_b32_e32 v6, 16, v15
	v_fma_f32 v3, v155, v3, v6
	v_cvt_pk_bf16_f32 v4, v3, v3
	global_store_short v1, v4, s[18:19]
	s_add_u32 s18, s18, s20
	s_addc_u32 s19, s19, s21
	v_lshlrev_b32_e32 v6, 16, v16
	v_fma_f32 v3, v156, v3, v6
	v_cvt_pk_bf16_f32 v5, v3, v3
	global_store_short v1, v5, s[18:19]
	s_add_u32 s18, s18, s20
	s_addc_u32 s19, s19, s21
	v_lshlrev_b32_e32 v6, 16, v17
	v_fma_f32 v3, v157, v3, v6
	v_cvt_pk_bf16_f32 v4, v3, v3
	global_store_short v1, v4, s[18:19]
	s_add_u32 s18, s18, s20
	s_addc_u32 s19, s19, s21
	v_lshlrev_b32_e32 v6, 16, v18
	v_fma_f32 v3, v158, v3, v6
	v_cvt_pk_bf16_f32 v5, v3, v3
	global_store_short v1, v5, s[18:19]
	s_add_u32 s18, s18, s20
	s_addc_u32 s19, s19, s21
	v_lshlrev_b32_e32 v6, 16, v19
	v_fma_f32 v3, v159, v3, v6
	s_waitcnt lgkmcnt(0)
	ds_read_b32 v148, v2 offset:6144
	ds_read_b32 v149, v2 offset:6400
	ds_read_b32 v150, v2 offset:6656
	ds_read_b32 v151, v2 offset:6912
	ds_read_b32 v152, v2 offset:7168
	ds_read_b32 v153, v2 offset:7424
	ds_read_b32 v154, v2 offset:7680
	ds_read_b32 v155, v2 offset:7936
	ds_read_b32 v156, v2 offset:8192
	ds_read_b32 v157, v2 offset:8448
	ds_read_b32 v158, v2 offset:8704
	ds_read_b32 v159, v2 offset:8960
	v_cvt_pk_bf16_f32 v4, v3, v3
	global_store_short v1, v4, s[18:19]
	s_add_u32 s18, s18, s20
	s_addc_u32 s19, s19, s21
	v_lshlrev_b32_e32 v6, 16, v20
	v_fma_f32 v3, v160, v3, v6
	v_cvt_pk_bf16_f32 v5, v3, v3
	global_store_short v1, v5, s[18:19]
	s_add_u32 s18, s18, s20
	s_addc_u32 s19, s19, s21
	v_lshlrev_b32_e32 v6, 16, v21
	v_fma_f32 v3, v161, v3, v6
	v_cvt_pk_bf16_f32 v4, v3, v3
	global_store_short v1, v4, s[18:19]
	s_add_u32 s18, s18, s20
	s_addc_u32 s19, s19, s21
	v_lshlrev_b32_e32 v6, 16, v22
	v_fma_f32 v3, v162, v3, v6
	v_cvt_pk_bf16_f32 v5, v3, v3
	global_store_short v1, v5, s[18:19]
	s_add_u32 s18, s18, s20
	s_addc_u32 s19, s19, s21
	v_lshlrev_b32_e32 v6, 16, v23
	v_fma_f32 v3, v163, v3, v6
	v_cvt_pk_bf16_f32 v4, v3, v3
	global_store_short v1, v4, s[18:19]
	s_add_u32 s18, s18, s20
	s_addc_u32 s19, s19, s21
	v_lshlrev_b32_e32 v6, 16, v24
	v_fma_f32 v3, v164, v3, v6
	v_cvt_pk_bf16_f32 v5, v3, v3
	global_store_short v1, v5, s[18:19]
	s_add_u32 s18, s18, s20
	s_addc_u32 s19, s19, s21
	v_lshlrev_b32_e32 v6, 16, v25
	v_fma_f32 v3, v165, v3, v6
	v_cvt_pk_bf16_f32 v4, v3, v3
	global_store_short v1, v4, s[18:19]
	s_add_u32 s18, s18, s20
	s_addc_u32 s19, s19, s21
	v_lshlrev_b32_e32 v6, 16, v26
	v_fma_f32 v3, v166, v3, v6
	v_cvt_pk_bf16_f32 v5, v3, v3
	global_store_short v1, v5, s[18:19]
	s_add_u32 s18, s18, s20
	s_addc_u32 s19, s19, s21
	v_lshlrev_b32_e32 v6, 16, v27
	v_fma_f32 v3, v167, v3, v6
	v_cvt_pk_bf16_f32 v4, v3, v3
	global_store_short v1, v4, s[18:19]
	s_add_u32 s18, s18, s20
	s_addc_u32 s19, s19, s21
	v_lshlrev_b32_e32 v6, 16, v28
	v_fma_f32 v3, v168, v3, v6
	v_cvt_pk_bf16_f32 v5, v3, v3
	global_store_short v1, v5, s[18:19]
	s_add_u32 s18, s18, s20
	s_addc_u32 s19, s19, s21
	v_lshlrev_b32_e32 v6, 16, v29
	v_fma_f32 v3, v169, v3, v6
	v_cvt_pk_bf16_f32 v4, v3, v3
	global_store_short v1, v4, s[18:19]
	s_add_u32 s18, s18, s20
	s_addc_u32 s19, s19, s21
	v_lshlrev_b32_e32 v6, 16, v30
	v_fma_f32 v3, v170, v3, v6
	v_cvt_pk_bf16_f32 v5, v3, v3
	global_store_short v1, v5, s[18:19]
	s_add_u32 s18, s18, s20
	s_addc_u32 s19, s19, s21
	v_lshlrev_b32_e32 v6, 16, v31
	v_fma_f32 v3, v171, v3, v6
	s_waitcnt lgkmcnt(0)
; __device__ __forceinline__ float bf2f(bf16_t b) { return __uint_as_float(((unsigned)b) << 16); }
; __device__ __forceinline__ bf16_t f2bf(float f) { unsigned u = __float_as_uint(f); return (bf16_t)((u + 0x7fffu + ((u >> 16) & 1u)) >> 16); }
; __device__ void phase_scan(const Params& p) {
;     ...
; #pragma unroll 1
;             for (int st = 0; st < NCH; st += 64) {
;                 bf16_t ub[64]; float db[64];
; #pragma unroll
;                 for (int i = 0; i < 64; ++i) { ub[i] = up[(long)(st + i) * step * 32768]; db[i] = dp[(long)(st + i) * step * 256]; }
; #pragma unroll
;                 for (int i = 0; i < 64; ++i) { sp[(long)(st + i) * step * 32768] = f2bf(s); s = db[i] * s + bf2f(ub[i]); }
;             }
	ds_read_b32 v160, v2 offset:9216
	ds_read_b32 v161, v2 offset:9472
	ds_read_b32 v162, v2 offset:9728
	ds_read_b32 v163, v2 offset:9984
	ds_read_b32 v164, v2 offset:10240
	ds_read_b32 v165, v2 offset:10496
	ds_read_b32 v166, v2 offset:10752
	ds_read_b32 v167, v2 offset:11008
	ds_read_b32 v168, v2 offset:11264
	ds_read_b32 v169, v2 offset:11520
	ds_read_b32 v170, v2 offset:11776
	ds_read_b32 v171, v2 offset:12032
	v_cvt_pk_bf16_f32 v4, v3, v3
	global_store_short v1, v4, s[18:19]
	s_add_u32 s18, s18, s20
	s_addc_u32 s19, s19, s21
	v_lshlrev_b32_e32 v6, 16, v32
	v_fma_f32 v3, v148, v3, v6
	v_cvt_pk_bf16_f32 v5, v3, v3
	global_store_short v1, v5, s[18:19]
	s_add_u32 s18, s18, s20
	s_addc_u32 s19, s19, s21
	v_lshlrev_b32_e32 v6, 16, v33
	v_fma_f32 v3, v149, v3, v6
	v_cvt_pk_bf16_f32 v4, v3, v3
	global_store_short v1, v4, s[18:19]
	s_add_u32 s18, s18, s20
	s_addc_u32 s19, s19, s21
	v_lshlrev_b32_e32 v6, 16, v34
	v_fma_f32 v3, v150, v3, v6
	v_cvt_pk_bf16_f32 v5, v3, v3
	global_store_short v1, v5, s[18:19]
	s_add_u32 s18, s18, s20
	s_addc_u32 s19, s19, s21
	v_lshlrev_b32_e32 v6, 16, v35
	v_fma_f32 v3, v151, v3, v6
	v_cvt_pk_bf16_f32 v4, v3, v3
	global_store_short v1, v4, s[18:19]
	s_add_u32 s18, s18, s20
	s_addc_u32 s19, s19, s21
	v_lshlrev_b32_e32 v6, 16, v36
	v_fma_f32 v3, v152, v3, v6
	v_cvt_pk_bf16_f32 v5, v3, v3
	global_store_short v1, v5, s[18:19]
	s_add_u32 s18, s18, s20
	s_addc_u32 s19, s19, s21
	v_lshlrev_b32_e32 v6, 16, v37
	v_fma_f32 v3, v153, v3, v6
	v_cvt_pk_bf16_f32 v4, v3, v3
	global_store_short v1, v4, s[18:19]
	s_add_u32 s18, s18, s20
	s_addc_u32 s19, s19, s21
	v_lshlrev_b32_e32 v6, 16, v38
	v_fma_f32 v3, v154, v3, v6
	v_cvt_pk_bf16_f32 v5, v3, v3
	global_store_short v1, v5, s[18:19]
	s_add_u32 s18, s18, s20
	s_addc_u32 s19, s19, s21
	v_lshlrev_b32_e32 v6, 16, v39
	v_fma_f32 v3, v155, v3, v6
	v_cvt_pk_bf16_f32 v4, v3, v3
	global_store_short v1, v4, s[18:19]
	s_add_u32 s18, s18, s20
	s_addc_u32 s19, s19, s21
	v_lshlrev_b32_e32 v6, 16, v40
	v_fma_f32 v3, v156, v3, v6
	v_cvt_pk_bf16_f32 v5, v3, v3
	global_store_short v1, v5, s[18:19]
	s_add_u32 s18, s18, s20
	s_addc_u32 s19, s19, s21
	v_lshlrev_b32_e32 v6, 16, v41
	v_fma_f32 v3, v157, v3, v6
	v_cvt_pk_bf16_f32 v4, v3, v3
	global_store_short v1, v4, s[18:19]
	s_add_u32 s18, s18, s20
	s_addc_u32 s19, s19, s21
	v_lshlrev_b32_e32 v6, 16, v42
	v_fma_f32 v3, v158, v3, v6
	v_cvt_pk_bf16_f32 v5, v3, v3
	global_store_short v1, v5, s[18:19]
	s_add_u32 s18, s18, s20
	s_addc_u32 s19, s19, s21
	v_lshlrev_b32_e32 v6, 16, v43
	v_fma_f32 v3, v159, v3, v6
	s_waitcnt lgkmcnt(0)
	ds_read_b32 v148, v2 offset:12288
	ds_read_b32 v149, v2 offset:12544
	ds_read_b32 v150, v2 offset:12800
	ds_read_b32 v151, v2 offset:13056
	ds_read_b32 v152, v2 offset:13312
	ds_read_b32 v153, v2 offset:13568
	ds_read_b32 v154, v2 offset:13824
	ds_read_b32 v155, v2 offset:14080
	ds_read_b32 v156, v2 offset:14336
	ds_read_b32 v157, v2 offset:14592
	ds_read_b32 v158, v2 offset:14848
	ds_read_b32 v159, v2 offset:15104
	v_cvt_pk_bf16_f32 v4, v3, v3
	global_store_short v1, v4, s[18:19]
	s_add_u32 s18, s18, s20
	s_addc_u32 s19, s19, s21
	v_lshlrev_b32_e32 v6, 16, v44
	v_fma_f32 v3, v160, v3, v6
	v_cvt_pk_bf16_f32 v5, v3, v3
	global_store_short v1, v5, s[18:19]
	s_add_u32 s18, s18, s20
	s_addc_u32 s19, s19, s21
	v_lshlrev_b32_e32 v6, 16, v45
	v_fma_f32 v3, v161, v3, v6
	v_cvt_pk_bf16_f32 v4, v3, v3
	global_store_short v1, v4, s[18:19]
	s_add_u32 s18, s18, s20
	s_addc_u32 s19, s19, s21
	v_lshlrev_b32_e32 v6, 16, v46
	v_fma_f32 v3, v162, v3, v6
	v_cvt_pk_bf16_f32 v5, v3, v3
	global_store_short v1, v5, s[18:19]
	s_add_u32 s18, s18, s20
	s_addc_u32 s19, s19, s21
	v_lshlrev_b32_e32 v6, 16, v47
	v_fma_f32 v3, v163, v3, v6
	v_cvt_pk_bf16_f32 v4, v3, v3
	global_store_short v1, v4, s[18:19]
	s_add_u32 s18, s18, s20
	s_addc_u32 s19, s19, s21
	v_lshlrev_b32_e32 v6, 16, v48
	v_fma_f32 v3, v164, v3, v6
	v_cvt_pk_bf16_f32 v5, v3, v3
	global_store_short v1, v5, s[18:19]
	s_add_u32 s18, s18, s20
	s_addc_u32 s19, s19, s21
	v_lshlrev_b32_e32 v6, 16, v49
	v_fma_f32 v3, v165, v3, v6
	v_cvt_pk_bf16_f32 v4, v3, v3
	global_store_short v1, v4, s[18:19]
	s_add_u32 s18, s18, s20
	s_addc_u32 s19, s19, s21
	v_lshlrev_b32_e32 v6, 16, v50
	v_fma_f32 v3, v166, v3, v6
	v_cvt_pk_bf16_f32 v5, v3, v3
	global_store_short v1, v5, s[18:19]
	s_add_u32 s18, s18, s20
	s_addc_u32 s19, s19, s21
	v_lshlrev_b32_e32 v6, 16, v51
	v_fma_f32 v3, v167, v3, v6
	v_cvt_pk_bf16_f32 v4, v3, v3
	global_store_short v1, v4, s[18:19]
	s_add_u32 s18, s18, s20
	s_addc_u32 s19, s19, s21
	v_lshlrev_b32_e32 v6, 16, v52
	v_fma_f32 v3, v168, v3, v6
	v_cvt_pk_bf16_f32 v5, v3, v3
	global_store_short v1, v5, s[18:19]
	s_add_u32 s18, s18, s20
	s_addc_u32 s19, s19, s21
	v_lshlrev_b32_e32 v6, 16, v53
	v_fma_f32 v3, v169, v3, v6
	v_cvt_pk_bf16_f32 v4, v3, v3
	global_store_short v1, v4, s[18:19]
	s_add_u32 s18, s18, s20
	s_addc_u32 s19, s19, s21
	v_lshlrev_b32_e32 v6, 16, v54
	v_fma_f32 v3, v170, v3, v6
	v_cvt_pk_bf16_f32 v5, v3, v3
	global_store_short v1, v5, s[18:19]
	s_add_u32 s18, s18, s20
	s_addc_u32 s19, s19, s21
	v_lshlrev_b32_e32 v6, 16, v55
	v_fma_f32 v3, v171, v3, v6
	s_waitcnt lgkmcnt(0)
; __device__ __forceinline__ float bf2f(bf16_t b) { return __uint_as_float(((unsigned)b) << 16); }
; __device__ __forceinline__ bf16_t f2bf(float f) { unsigned u = __float_as_uint(f); return (bf16_t)((u + 0x7fffu + ((u >> 16) & 1u)) >> 16); }
; __device__ void phase_scan(const Params& p) {
;     ...
; #pragma unroll 1
;             for (int st = 0; st < NCH; st += 64) {
;                 bf16_t ub[64]; float db[64];
; #pragma unroll
;                 for (int i = 0; i < 64; ++i) { ub[i] = up[(long)(st + i) * step * 32768]; db[i] = dp[(long)(st + i) * step * 256]; }
; #pragma unroll
;                 for (int i = 0; i < 64; ++i) { sp[(long)(st + i) * step * 32768] = f2bf(s); s = db[i] * s + bf2f(ub[i]); }
;             }
	ds_read_b32 v160, v2 offset:15360
	ds_read_b32 v161, v2 offset:15616
	ds_read_b32 v162, v2 offset:15872
	ds_read_b32 v163, v2 offset:16128
	ds_read_b32 v164, v2 offset:16384
	ds_read_b32 v165, v2 offset:16640
	ds_read_b32 v166, v2 offset:16896
	ds_read_b32 v167, v2 offset:17152
	ds_read_b32 v168, v2 offset:17408
	ds_read_b32 v169, v2 offset:17664
	ds_read_b32 v170, v2 offset:17920
	ds_read_b32 v171, v2 offset:18176
	v_cvt_pk_bf16_f32 v4, v3, v3
	global_store_short v1, v4, s[18:19]
	s_add_u32 s18, s18, s20
	s_addc_u32 s19, s19, s21
	v_lshlrev_b32_e32 v6, 16, v56
	v_fma_f32 v3, v148, v3, v6
	v_cvt_pk_bf16_f32 v5, v3, v3
	global_store_short v1, v5, s[18:19]
	s_add_u32 s18, s18, s20
	s_addc_u32 s19, s19, s21
	v_lshlrev_b32_e32 v6, 16, v57
	v_fma_f32 v3, v149, v3, v6
	v_cvt_pk_bf16_f32 v4, v3, v3
	global_store_short v1, v4, s[18:19]
	s_add_u32 s18, s18, s20
	s_addc_u32 s19, s19, s21
	v_lshlrev_b32_e32 v6, 16, v58
	v_fma_f32 v3, v150, v3, v6
	v_cvt_pk_bf16_f32 v5, v3, v3
	global_store_short v1, v5, s[18:19]
	s_add_u32 s18, s18, s20
	s_addc_u32 s19, s19, s21
	v_lshlrev_b32_e32 v6, 16, v59
	v_fma_f32 v3, v151, v3, v6
	v_cvt_pk_bf16_f32 v4, v3, v3
	global_store_short v1, v4, s[18:19]
	s_add_u32 s18, s18, s20
	s_addc_u32 s19, s19, s21
	v_lshlrev_b32_e32 v6, 16, v60
	v_fma_f32 v3, v152, v3, v6
	v_cvt_pk_bf16_f32 v5, v3, v3
	global_store_short v1, v5, s[18:19]
	s_add_u32 s18, s18, s20
	s_addc_u32 s19, s19, s21
	v_lshlrev_b32_e32 v6, 16, v61
	v_fma_f32 v3, v153, v3, v6
	v_cvt_pk_bf16_f32 v4, v3, v3
	global_store_short v1, v4, s[18:19]
	s_add_u32 s18, s18, s20
	s_addc_u32 s19, s19, s21
	v_lshlrev_b32_e32 v6, 16, v62
	v_fma_f32 v3, v154, v3, v6
	v_cvt_pk_bf16_f32 v5, v3, v3
	global_store_short v1, v5, s[18:19]
	s_add_u32 s18, s18, s20
	s_addc_u32 s19, s19, s21
	v_lshlrev_b32_e32 v6, 16, v63
	v_fma_f32 v3, v155, v3, v6
	v_cvt_pk_bf16_f32 v4, v3, v3
	global_store_short v1, v4, s[18:19]
	s_add_u32 s18, s18, s20
	s_addc_u32 s19, s19, s21
	v_lshlrev_b32_e32 v6, 16, v64
	v_fma_f32 v3, v156, v3, v6
	v_cvt_pk_bf16_f32 v5, v3, v3
	global_store_short v1, v5, s[18:19]
	s_add_u32 s18, s18, s20
	s_addc_u32 s19, s19, s21
	v_lshlrev_b32_e32 v6, 16, v65
	v_fma_f32 v3, v157, v3, v6
	v_cvt_pk_bf16_f32 v4, v3, v3
	global_store_short v1, v4, s[18:19]
	s_add_u32 s18, s18, s20
	s_addc_u32 s19, s19, s21
	v_lshlrev_b32_e32 v6, 16, v66
	v_fma_f32 v3, v158, v3, v6
	v_cvt_pk_bf16_f32 v5, v3, v3
	global_store_short v1, v5, s[18:19]
	s_add_u32 s18, s18, s20
	s_addc_u32 s19, s19, s21
	v_lshlrev_b32_e32 v6, 16, v67
	v_fma_f32 v3, v159, v3, v6
	s_waitcnt lgkmcnt(0)
	ds_read_b32 v148, v2 offset:18432
	ds_read_b32 v149, v2 offset:18688
	ds_read_b32 v150, v2 offset:18944
	ds_read_b32 v151, v2 offset:19200
	ds_read_b32 v152, v2 offset:19456
	ds_read_b32 v153, v2 offset:19712
	ds_read_b32 v154, v2 offset:19968
	ds_read_b32 v155, v2 offset:20224
	ds_read_b32 v156, v2 offset:20480
	ds_read_b32 v157, v2 offset:20736
	ds_read_b32 v158, v2 offset:20992
	ds_read_b32 v159, v2 offset:21248
	v_cvt_pk_bf16_f32 v4, v3, v3
	global_store_short v1, v4, s[18:19]
	s_add_u32 s18, s18, s20
	s_addc_u32 s19, s19, s21
	v_lshlrev_b32_e32 v6, 16, v68
	v_fma_f32 v3, v160, v3, v6
	v_cvt_pk_bf16_f32 v5, v3, v3
	global_store_short v1, v5, s[18:19]
	s_add_u32 s18, s18, s20
	s_addc_u32 s19, s19, s21
	v_lshlrev_b32_e32 v6, 16, v69
	v_fma_f32 v3, v161, v3, v6
	v_cvt_pk_bf16_f32 v4, v3, v3
	global_store_short v1, v4, s[18:19]
	s_add_u32 s18, s18, s20
	s_addc_u32 s19, s19, s21
	v_lshlrev_b32_e32 v6, 16, v70
	v_fma_f32 v3, v162, v3, v6
	v_cvt_pk_bf16_f32 v5, v3, v3
	global_store_short v1, v5, s[18:19]
	s_add_u32 s18, s18, s20
	s_addc_u32 s19, s19, s21
	v_lshlrev_b32_e32 v6, 16, v71
	v_fma_f32 v3, v163, v3, v6
	s_waitcnt vmcnt(63)
	v_cvt_pk_bf16_f32 v4, v3, v3
	global_store_short v1, v4, s[18:19]
	s_add_u32 s18, s18, s20
	s_addc_u32 s19, s19, s21
	v_lshlrev_b32_e32 v6, 16, v72
	v_fma_f32 v3, v164, v3, v6
	v_cvt_pk_bf16_f32 v5, v3, v3
	global_store_short v1, v5, s[18:19]
	s_add_u32 s18, s18, s20
	s_addc_u32 s19, s19, s21
	v_lshlrev_b32_e32 v6, 16, v73
	v_fma_f32 v3, v165, v3, v6
	v_cvt_pk_bf16_f32 v4, v3, v3
	global_store_short v1, v4, s[18:19]
	s_add_u32 s18, s18, s20
	s_addc_u32 s19, s19, s21
	v_lshlrev_b32_e32 v6, 16, v74
	v_fma_f32 v3, v166, v3, v6
	v_cvt_pk_bf16_f32 v5, v3, v3
	global_store_short v1, v5, s[18:19]
	s_add_u32 s18, s18, s20
	s_addc_u32 s19, s19, s21
	v_lshlrev_b32_e32 v6, 16, v75
	v_fma_f32 v3, v167, v3, v6
	v_cvt_pk_bf16_f32 v4, v3, v3
	global_store_short v1, v4, s[18:19]
	s_add_u32 s18, s18, s20
	s_addc_u32 s19, s19, s21
	v_lshlrev_b32_e32 v6, 16, v76
	v_fma_f32 v3, v168, v3, v6
	v_cvt_pk_bf16_f32 v5, v3, v3
	global_store_short v1, v5, s[18:19]
	s_add_u32 s18, s18, s20
	s_addc_u32 s19, s19, s21
	v_lshlrev_b32_e32 v6, 16, v77
	v_fma_f32 v3, v169, v3, v6
	v_cvt_pk_bf16_f32 v4, v3, v3
	global_store_short v1, v4, s[18:19]
	s_add_u32 s18, s18, s20
	s_addc_u32 s19, s19, s21
	v_lshlrev_b32_e32 v6, 16, v78
	v_fma_f32 v3, v170, v3, v6
	v_cvt_pk_bf16_f32 v5, v3, v3
	global_store_short v1, v5, s[18:19]
	s_add_u32 s18, s18, s20
	s_addc_u32 s19, s19, s21
	v_lshlrev_b32_e32 v6, 16, v79
	v_fma_f32 v3, v171, v3, v6
	s_waitcnt lgkmcnt(0)
; __device__ __forceinline__ float bf2f(bf16_t b) { return __uint_as_float(((unsigned)b) << 16); }
; __device__ __forceinline__ bf16_t f2bf(float f) { unsigned u = __float_as_uint(f); return (bf16_t)((u + 0x7fffu + ((u >> 16) & 1u)) >> 16); }
; __device__ void phase_scan(const Params& p) {
;     ...
; #pragma unroll 1
;             for (int st = 0; st < NCH; st += 64) {
;                 bf16_t ub[64]; float db[64];
; #pragma unroll
;                 for (int i = 0; i < 64; ++i) { ub[i] = up[(long)(st + i) * step * 32768]; db[i] = dp[(long)(st + i) * step * 256]; }
; #pragma unroll
;                 for (int i = 0; i < 64; ++i) { sp[(long)(st + i) * step * 32768] = f2bf(s); s = db[i] * s + bf2f(ub[i]); }
;             }
	ds_read_b32 v160, v2 offset:21504
	ds_read_b32 v161, v2 offset:21760
	ds_read_b32 v162, v2 offset:22016
	ds_read_b32 v163, v2 offset:22272
	ds_read_b32 v164, v2 offset:22528
	ds_read_b32 v165, v2 offset:22784
	ds_read_b32 v166, v2 offset:23040
	ds_read_b32 v167, v2 offset:23296
	ds_read_b32 v168, v2 offset:23552
	ds_read_b32 v169, v2 offset:23808
	ds_read_b32 v170, v2 offset:24064
	ds_read_b32 v171, v2 offset:24320
	v_cvt_pk_bf16_f32 v4, v3, v3
	global_store_short v1, v4, s[18:19]
	s_add_u32 s18, s18, s20
	s_addc_u32 s19, s19, s21
	v_lshlrev_b32_e32 v6, 16, v80
	v_fma_f32 v3, v148, v3, v6
	v_cvt_pk_bf16_f32 v5, v3, v3
	global_store_short v1, v5, s[18:19]
	s_add_u32 s18, s18, s20
	s_addc_u32 s19, s19, s21
	v_lshlrev_b32_e32 v6, 16, v81
	v_fma_f32 v3, v149, v3, v6
	v_cvt_pk_bf16_f32 v4, v3, v3
	global_store_short v1, v4, s[18:19]
	s_add_u32 s18, s18, s20
	s_addc_u32 s19, s19, s21
	v_lshlrev_b32_e32 v6, 16, v82
	v_fma_f32 v3, v150, v3, v6
	v_cvt_pk_bf16_f32 v5, v3, v3
	global_store_short v1, v5, s[18:19]
	s_add_u32 s18, s18, s20
	s_addc_u32 s19, s19, s21
	v_lshlrev_b32_e32 v6, 16, v83
	v_fma_f32 v3, v151, v3, v6
	v_cvt_pk_bf16_f32 v4, v3, v3
	global_store_short v1, v4, s[18:19]
	s_add_u32 s18, s18, s20
	s_addc_u32 s19, s19, s21
	v_lshlrev_b32_e32 v6, 16, v84
	v_fma_f32 v3, v152, v3, v6
	v_cvt_pk_bf16_f32 v5, v3, v3
	global_store_short v1, v5, s[18:19]
	s_add_u32 s18, s18, s20
	s_addc_u32 s19, s19, s21
	v_lshlrev_b32_e32 v6, 16, v85
	v_fma_f32 v3, v153, v3, v6
	v_cvt_pk_bf16_f32 v4, v3, v3
	global_store_short v1, v4, s[18:19]
	s_add_u32 s18, s18, s20
	s_addc_u32 s19, s19, s21
	v_lshlrev_b32_e32 v6, 16, v86
	v_fma_f32 v3, v154, v3, v6
	v_cvt_pk_bf16_f32 v5, v3, v3
	global_store_short v1, v5, s[18:19]
	s_add_u32 s18, s18, s20
	s_addc_u32 s19, s19, s21
	v_lshlrev_b32_e32 v6, 16, v87
	v_fma_f32 v3, v155, v3, v6
	v_cvt_pk_bf16_f32 v4, v3, v3
	global_store_short v1, v4, s[18:19]
	s_add_u32 s18, s18, s20
	s_addc_u32 s19, s19, s21
	v_lshlrev_b32_e32 v6, 16, v88
	v_fma_f32 v3, v156, v3, v6
	v_cvt_pk_bf16_f32 v5, v3, v3
	global_store_short v1, v5, s[18:19]
	s_add_u32 s18, s18, s20
	s_addc_u32 s19, s19, s21
	v_lshlrev_b32_e32 v6, 16, v89
	v_fma_f32 v3, v157, v3, v6
	v_cvt_pk_bf16_f32 v4, v3, v3
	global_store_short v1, v4, s[18:19]
	s_add_u32 s18, s18, s20
	s_addc_u32 s19, s19, s21
	v_lshlrev_b32_e32 v6, 16, v90
	v_fma_f32 v3, v158, v3, v6
	v_cvt_pk_bf16_f32 v5, v3, v3
	global_store_short v1, v5, s[18:19]
	s_add_u32 s18, s18, s20
	s_addc_u32 s19, s19, s21
	v_lshlrev_b32_e32 v6, 16, v91
	v_fma_f32 v3, v159, v3, v6
	s_waitcnt lgkmcnt(0)
	ds_read_b32 v148, v2 offset:24576
	ds_read_b32 v149, v2 offset:24832
	ds_read_b32 v150, v2 offset:25088
	ds_read_b32 v151, v2 offset:25344
	ds_read_b32 v152, v2 offset:25600
	ds_read_b32 v153, v2 offset:25856
	ds_read_b32 v154, v2 offset:26112
	ds_read_b32 v155, v2 offset:26368
	ds_read_b32 v156, v2 offset:26624
	ds_read_b32 v157, v2 offset:26880
	ds_read_b32 v158, v2 offset:27136
	ds_read_b32 v159, v2 offset:27392
	v_cvt_pk_bf16_f32 v4, v3, v3
	global_store_short v1, v4, s[18:19]
	s_add_u32 s18, s18, s20
	s_addc_u32 s19, s19, s21
	v_lshlrev_b32_e32 v6, 16, v92
	v_fma_f32 v3, v160, v3, v6
	v_cvt_pk_bf16_f32 v5, v3, v3
	global_store_short v1, v5, s[18:19]
	s_add_u32 s18, s18, s20
	s_addc_u32 s19, s19, s21
	v_lshlrev_b32_e32 v6, 16, v93
	v_fma_f32 v3, v161, v3, v6
	v_cvt_pk_bf16_f32 v4, v3, v3
	global_store_short v1, v4, s[18:19]
	s_add_u32 s18, s18, s20
	s_addc_u32 s19, s19, s21
	v_lshlrev_b32_e32 v6, 16, v94
	v_fma_f32 v3, v162, v3, v6
	v_cvt_pk_bf16_f32 v5, v3, v3
	global_store_short v1, v5, s[18:19]
	s_add_u32 s18, s18, s20
	s_addc_u32 s19, s19, s21
	v_lshlrev_b32_e32 v6, 16, v95
	v_fma_f32 v3, v163, v3, v6
	v_cvt_pk_bf16_f32 v4, v3, v3
	global_store_short v1, v4, s[18:19]
	s_add_u32 s18, s18, s20
	s_addc_u32 s19, s19, s21
	v_lshlrev_b32_e32 v6, 16, v96
	v_fma_f32 v3, v164, v3, v6
	v_cvt_pk_bf16_f32 v5, v3, v3
	global_store_short v1, v5, s[18:19]
	s_add_u32 s18, s18, s20
	s_addc_u32 s19, s19, s21
	v_lshlrev_b32_e32 v6, 16, v97
	v_fma_f32 v3, v165, v3, v6
	v_cvt_pk_bf16_f32 v4, v3, v3
	global_store_short v1, v4, s[18:19]
	s_add_u32 s18, s18, s20
	s_addc_u32 s19, s19, s21
	v_lshlrev_b32_e32 v6, 16, v98
	v_fma_f32 v3, v166, v3, v6
	v_cvt_pk_bf16_f32 v5, v3, v3
	global_store_short v1, v5, s[18:19]
	s_add_u32 s18, s18, s20
	s_addc_u32 s19, s19, s21
	v_lshlrev_b32_e32 v6, 16, v99
	v_fma_f32 v3, v167, v3, v6
	v_cvt_pk_bf16_f32 v4, v3, v3
	global_store_short v1, v4, s[18:19]
	s_add_u32 s18, s18, s20
	s_addc_u32 s19, s19, s21
	v_lshlrev_b32_e32 v6, 16, v100
	v_fma_f32 v3, v168, v3, v6
	v_cvt_pk_bf16_f32 v5, v3, v3
	global_store_short v1, v5, s[18:19]
	s_add_u32 s18, s18, s20
	s_addc_u32 s19, s19, s21
	v_lshlrev_b32_e32 v6, 16, v101
	v_fma_f32 v3, v169, v3, v6
	v_cvt_pk_bf16_f32 v4, v3, v3
	global_store_short v1, v4, s[18:19]
	s_add_u32 s18, s18, s20
	s_addc_u32 s19, s19, s21
	v_lshlrev_b32_e32 v6, 16, v102
	v_fma_f32 v3, v170, v3, v6
	v_cvt_pk_bf16_f32 v5, v3, v3
	global_store_short v1, v5, s[18:19]
	s_add_u32 s18, s18, s20
	s_addc_u32 s19, s19, s21
	v_lshlrev_b32_e32 v6, 16, v103
	v_fma_f32 v3, v171, v3, v6
	s_waitcnt lgkmcnt(0)
; __device__ __forceinline__ float bf2f(bf16_t b) { return __uint_as_float(((unsigned)b) << 16); }
; __device__ __forceinline__ bf16_t f2bf(float f) { unsigned u = __float_as_uint(f); return (bf16_t)((u + 0x7fffu + ((u >> 16) & 1u)) >> 16); }
; __device__ void phase_scan(const Params& p) {
;     ...
; #pragma unroll 1
;             for (int st = 0; st < NCH; st += 64) {
;                 bf16_t ub[64]; float db[64];
; #pragma unroll
;                 for (int i = 0; i < 64; ++i) { ub[i] = up[(long)(st + i) * step * 32768]; db[i] = dp[(long)(st + i) * step * 256]; }
; #pragma unroll
;                 for (int i = 0; i < 64; ++i) { sp[(long)(st + i) * step * 32768] = f2bf(s); s = db[i] * s + bf2f(ub[i]); }
;             }
	ds_read_b32 v160, v2 offset:27648
	ds_read_b32 v161, v2 offset:27904
	ds_read_b32 v162, v2 offset:28160
	ds_read_b32 v163, v2 offset:28416
	ds_read_b32 v164, v2 offset:28672
	ds_read_b32 v165, v2 offset:28928
	ds_read_b32 v166, v2 offset:29184
	ds_read_b32 v167, v2 offset:29440
	ds_read_b32 v168, v2 offset:29696
	ds_read_b32 v169, v2 offset:29952
	ds_read_b32 v170, v2 offset:30208
	ds_read_b32 v171, v2 offset:30464
	v_cvt_pk_bf16_f32 v4, v3, v3
	global_store_short v1, v4, s[18:19]
	s_add_u32 s18, s18, s20
	s_addc_u32 s19, s19, s21
	v_lshlrev_b32_e32 v6, 16, v104
	v_fma_f32 v3, v148, v3, v6
	v_cvt_pk_bf16_f32 v5, v3, v3
	global_store_short v1, v5, s[18:19]
	s_add_u32 s18, s18, s20
	s_addc_u32 s19, s19, s21
	v_lshlrev_b32_e32 v6, 16, v105
	v_fma_f32 v3, v149, v3, v6
	v_cvt_pk_bf16_f32 v4, v3, v3
	global_store_short v1, v4, s[18:19]
	s_add_u32 s18, s18, s20
	s_addc_u32 s19, s19, s21
	v_lshlrev_b32_e32 v6, 16, v106
	v_fma_f32 v3, v150, v3, v6
	v_cvt_pk_bf16_f32 v5, v3, v3
	global_store_short v1, v5, s[18:19]
	s_add_u32 s18, s18, s20
	s_addc_u32 s19, s19, s21
	v_lshlrev_b32_e32 v6, 16, v107
	v_fma_f32 v3, v151, v3, v6
	v_cvt_pk_bf16_f32 v4, v3, v3
	global_store_short v1, v4, s[18:19]
	s_add_u32 s18, s18, s20
	s_addc_u32 s19, s19, s21
	v_lshlrev_b32_e32 v6, 16, v108
	v_fma_f32 v3, v152, v3, v6
	v_cvt_pk_bf16_f32 v5, v3, v3
	global_store_short v1, v5, s[18:19]
	s_add_u32 s18, s18, s20
	s_addc_u32 s19, s19, s21
	v_lshlrev_b32_e32 v6, 16, v109
	v_fma_f32 v3, v153, v3, v6
	v_cvt_pk_bf16_f32 v4, v3, v3
	global_store_short v1, v4, s[18:19]
	s_add_u32 s18, s18, s20
	s_addc_u32 s19, s19, s21
	v_lshlrev_b32_e32 v6, 16, v110
	v_fma_f32 v3, v154, v3, v6
	v_cvt_pk_bf16_f32 v5, v3, v3
	global_store_short v1, v5, s[18:19]
	s_add_u32 s18, s18, s20
	s_addc_u32 s19, s19, s21
	v_lshlrev_b32_e32 v6, 16, v111
	v_fma_f32 v3, v155, v3, v6
	v_cvt_pk_bf16_f32 v4, v3, v3
	global_store_short v1, v4, s[18:19]
	s_add_u32 s18, s18, s20
	s_addc_u32 s19, s19, s21
	v_lshlrev_b32_e32 v6, 16, v112
	v_fma_f32 v3, v156, v3, v6
	v_cvt_pk_bf16_f32 v5, v3, v3
	global_store_short v1, v5, s[18:19]
	s_add_u32 s18, s18, s20
	s_addc_u32 s19, s19, s21
	v_lshlrev_b32_e32 v6, 16, v113
	v_fma_f32 v3, v157, v3, v6
	v_cvt_pk_bf16_f32 v4, v3, v3
	global_store_short v1, v4, s[18:19]
	s_add_u32 s18, s18, s20
	s_addc_u32 s19, s19, s21
	v_lshlrev_b32_e32 v6, 16, v114
	v_fma_f32 v3, v158, v3, v6
	v_cvt_pk_bf16_f32 v5, v3, v3
	global_store_short v1, v5, s[18:19]
	s_add_u32 s18, s18, s20
	s_addc_u32 s19, s19, s21
	v_lshlrev_b32_e32 v6, 16, v115
	v_fma_f32 v3, v159, v3, v6
	s_waitcnt lgkmcnt(0)
	ds_read_b32 v148, v2 offset:30720
	ds_read_b32 v149, v2 offset:30976
	ds_read_b32 v150, v2 offset:31232
	ds_read_b32 v151, v2 offset:31488
	ds_read_b32 v152, v2 offset:31744
	ds_read_b32 v153, v2 offset:32000
	ds_read_b32 v154, v2 offset:32256
	ds_read_b32 v155, v2 offset:32512
	v_cvt_pk_bf16_f32 v4, v3, v3
	global_store_short v1, v4, s[18:19]
	s_add_u32 s18, s18, s20
	s_addc_u32 s19, s19, s21
	v_lshlrev_b32_e32 v6, 16, v116
	v_fma_f32 v3, v160, v3, v6
	v_cvt_pk_bf16_f32 v5, v3, v3
	global_store_short v1, v5, s[18:19]
	s_add_u32 s18, s18, s20
	s_addc_u32 s19, s19, s21
	v_lshlrev_b32_e32 v6, 16, v117
	v_fma_f32 v3, v161, v3, v6
	v_cvt_pk_bf16_f32 v4, v3, v3
	global_store_short v1, v4, s[18:19]
	s_add_u32 s18, s18, s20
	s_addc_u32 s19, s19, s21
	v_lshlrev_b32_e32 v6, 16, v118
	v_fma_f32 v3, v162, v3, v6
	v_cvt_pk_bf16_f32 v5, v3, v3
	global_store_short v1, v5, s[18:19]
	s_add_u32 s18, s18, s20
	s_addc_u32 s19, s19, s21
	v_lshlrev_b32_e32 v6, 16, v119
	v_fma_f32 v3, v163, v3, v6
	v_cvt_pk_bf16_f32 v4, v3, v3
	global_store_short v1, v4, s[18:19]
	s_add_u32 s18, s18, s20
	s_addc_u32 s19, s19, s21
	v_lshlrev_b32_e32 v6, 16, v120
	v_fma_f32 v3, v164, v3, v6
	v_cvt_pk_bf16_f32 v5, v3, v3
	global_store_short v1, v5, s[18:19]
	s_add_u32 s18, s18, s20
	s_addc_u32 s19, s19, s21
	v_lshlrev_b32_e32 v6, 16, v121
	v_fma_f32 v3, v165, v3, v6
	v_cvt_pk_bf16_f32 v4, v3, v3
	global_store_short v1, v4, s[18:19]
	s_add_u32 s18, s18, s20
	s_addc_u32 s19, s19, s21
	v_lshlrev_b32_e32 v6, 16, v122
	v_fma_f32 v3, v166, v3, v6
	v_cvt_pk_bf16_f32 v5, v3, v3
	global_store_short v1, v5, s[18:19]
	s_add_u32 s18, s18, s20
	s_addc_u32 s19, s19, s21
	v_lshlrev_b32_e32 v6, 16, v123
	v_fma_f32 v3, v167, v3, v6
	v_cvt_pk_bf16_f32 v4, v3, v3
	global_store_short v1, v4, s[18:19]
	s_add_u32 s18, s18, s20
	s_addc_u32 s19, s19, s21
	v_lshlrev_b32_e32 v6, 16, v124
	v_fma_f32 v3, v168, v3, v6
	v_cvt_pk_bf16_f32 v5, v3, v3
	global_store_short v1, v5, s[18:19]
	s_add_u32 s18, s18, s20
	s_addc_u32 s19, s19, s21
	v_lshlrev_b32_e32 v6, 16, v125
	v_fma_f32 v3, v169, v3, v6
	v_cvt_pk_bf16_f32 v4, v3, v3
	global_store_short v1, v4, s[18:19]
	s_add_u32 s18, s18, s20
	s_addc_u32 s19, s19, s21
	v_lshlrev_b32_e32 v6, 16, v126
	v_fma_f32 v3, v170, v3, v6
	v_cvt_pk_bf16_f32 v5, v3, v3
	global_store_short v1, v5, s[18:19]
	s_add_u32 s18, s18, s20
	s_addc_u32 s19, s19, s21
	v_lshlrev_b32_e32 v6, 16, v127
	v_fma_f32 v3, v171, v3, v6
	s_waitcnt lgkmcnt(0)
	v_cvt_pk_bf16_f32 v4, v3, v3
	global_store_short v1, v4, s[18:19]
	s_add_u32 s18, s18, s20
	s_addc_u32 s19, s19, s21
	v_lshlrev_b32_e32 v6, 16, v128
	v_fma_f32 v3, v148, v3, v6
	v_cvt_pk_bf16_f32 v5, v3, v3
	global_store_short v1, v5, s[18:19]
	s_add_u32 s18, s18, s20
	s_addc_u32 s19, s19, s21
	v_lshlrev_b32_e32 v6, 16, v129
	v_fma_f32 v3, v149, v3, v6
	v_cvt_pk_bf16_f32 v4, v3, v3
	global_store_short v1, v4, s[18:19]
	s_add_u32 s18, s18, s20
	s_addc_u32 s19, s19, s21
	v_lshlrev_b32_e32 v6, 16, v130
	v_fma_f32 v3, v150, v3, v6
	v_cvt_pk_bf16_f32 v5, v3, v3
	global_store_short v1, v5, s[18:19]
	s_add_u32 s18, s18, s20
	s_addc_u32 s19, s19, s21
	v_lshlrev_b32_e32 v6, 16, v131
	v_fma_f32 v3, v151, v3, v6
	v_cvt_pk_bf16_f32 v4, v3, v3
	global_store_short v1, v4, s[18:19]
	s_add_u32 s18, s18, s20
	s_addc_u32 s19, s19, s21
	v_lshlrev_b32_e32 v6, 16, v132
	v_fma_f32 v3, v152, v3, v6
	v_cvt_pk_bf16_f32 v5, v3, v3
	global_store_short v1, v5, s[18:19]
	s_add_u32 s18, s18, s20
	s_addc_u32 s19, s19, s21
	v_lshlrev_b32_e32 v6, 16, v133
	v_fma_f32 v3, v153, v3, v6
	v_cvt_pk_bf16_f32 v4, v3, v3
	global_store_short v1, v4, s[18:19]
	s_add_u32 s18, s18, s20
	s_addc_u32 s19, s19, s21
	v_lshlrev_b32_e32 v6, 16, v134
	v_fma_f32 v3, v154, v3, v6
	v_cvt_pk_bf16_f32 v5, v3, v3
	global_store_short v1, v5, s[18:19]
	v_lshlrev_b32_e32 v6, 16, v135
	v_fma_f32 v3, v155, v3, v6
	s_cmp_eq_u32 s14, 0
	s_cbranch_scc0 .Lscan_done
	ds_write_b32 v7, v3
	s_waitcnt lgkmcnt(0)
	s_barrier
.Lscan_done:
	v_readlane_b32 s16, v184, 0
	v_readlane_b32 s17, v184, 1
	v_readlane_b32 s18, v184, 2
	v_readlane_b32 s19, v184, 3
	v_readlane_b32 s20, v184, 4
	v_readlane_b32 s21, v184, 5
	v_readlane_b32 s22, v184, 6
	v_readlane_b32 s23, v184, 7
	v_readlane_b32 s24, v184, 8
	v_readlane_b32 s25, v184, 9
	v_readlane_b32 s26, v184, 10
	v_readlane_b32 s27, v184, 11
	v_readlane_b32 s28, v184, 12
	v_readlane_b32 s29, v184, 13
	v_readlane_b32 s30, v184, 14
	v_readlane_b32 s31, v184, 15
	s_mov_b64 s[0:1], 0
